# GEMM K-loops (5 instances): blanket lgkmcnt(0) before each MFMA block replaced by counted waits at first use
# speedup vs baseline: 1.0174x; 1.0062x over previous
.LBB0_268:
	s_add_i32 s42, s20, 2
	s_add_u32 s22, s16, 0x80
	s_addc_u32 s21, s17, 0
	s_add_i32 s43, 0, 0x10000
	v_add_u32_e32 v142, s43, v170
	ds_read_b128 v[130:133], v142
	ds_read_b128 v[134:137], v142 offset:1024
	ds_read_b128 v[138:141], v142 offset:2048
	ds_read_b128 v[142:145], v142 offset:3072
	s_cmp_eq_u32 s66, s20
	s_cselect_b32 s20, s2, s22
	s_cselect_b32 s21, s3, s21
	s_cselect_b32 s23, s13, s25
	s_cselect_b32 s22, s12, s24
	v_lshl_add_u64 v[168:169], s[16:17], 0, v[164:165]
	s_add_i32 m0, s36, 0xc000
	ds_read_b128 v[176:179], v172
	ds_read_b128 v[180:183], v172 offset:1024
	ds_read_b128 v[184:187], v172 offset:2048
	ds_read_b128 v[188:191], v172 offset:3072
	ds_read_b128 v[192:195], v172 offset:4096
	ds_read_b128 v[196:199], v172 offset:5120
	ds_read_b128 v[200:203], v172 offset:6144
	ds_read_b128 v[204:207], v172 offset:7168
	global_load_lds_dwordx4 v[168:169], off
	v_lshl_add_u64 v[168:169], s[16:17], 0, v[166:167]
	s_add_i32 m0, s36, 0xe000
	s_nop 0
	global_load_lds_dwordx4 v[168:169], off
	s_waitcnt lgkmcnt(8)
	s_barrier
	s_setprio 1
	s_waitcnt lgkmcnt(7)
	v_mfma_f32_16x16x32_bf16 v[126:129], v[130:133], v[176:179], v[126:129]
	v_mfma_f32_16x16x32_bf16 v[122:125], v[138:141], v[176:179], v[122:125]
	s_waitcnt lgkmcnt(5)
	v_mfma_f32_16x16x32_bf16 v[114:117], v[130:133], v[184:187], v[114:117]
	v_mfma_f32_16x16x32_bf16 v[110:113], v[138:141], v[184:187], v[110:113]
	s_waitcnt lgkmcnt(3)
	v_mfma_f32_16x16x32_bf16 v[98:101], v[130:133], v[192:195], v[98:101]
	v_mfma_f32_16x16x32_bf16 v[94:97], v[138:141], v[192:195], v[94:97]
	s_waitcnt lgkmcnt(1)
	v_mfma_f32_16x16x32_bf16 v[82:85], v[130:133], v[200:203], v[82:85]
	v_mfma_f32_16x16x32_bf16 v[78:81], v[138:141], v[200:203], v[78:81]
	v_mfma_f32_16x16x32_bf16 v[126:129], v[134:137], v[180:183], v[126:129]
	v_mfma_f32_16x16x32_bf16 v[122:125], v[142:145], v[180:183], v[122:125]
	v_mfma_f32_16x16x32_bf16 v[114:117], v[134:137], v[188:191], v[114:117]
	v_mfma_f32_16x16x32_bf16 v[110:113], v[142:145], v[188:191], v[110:113]
	v_mfma_f32_16x16x32_bf16 v[98:101], v[134:137], v[196:199], v[98:101]
	v_mfma_f32_16x16x32_bf16 v[94:97], v[142:145], v[196:199], v[94:97]
	s_waitcnt lgkmcnt(0)
	v_mfma_f32_16x16x32_bf16 v[82:85], v[134:137], v[204:207], v[82:85]
	v_mfma_f32_16x16x32_bf16 v[78:81], v[142:145], v[204:207], v[78:81]
	s_setprio 0
	s_barrier
	s_add_i32 s44, 0, 0x14000
	v_add_u32_e32 v168, s44, v170
	s_add_i32 s43, s43, s35
	ds_read_b128 v[208:211], v168
	ds_read_b128 v[212:215], v168 offset:1024
	ds_read_b128 v[216:219], v168 offset:2048
	ds_read_b128 v[234:237], v168 offset:3072
	v_lshl_add_u64 v[168:169], s[22:23], 0, v[48:49]
	s_mov_b32 m0, s43
	v_lshl_add_u64 v[224:225], s[22:23], 0, v[146:147]
	global_load_lds_dwordx4 v[168:169], off
	s_add_i32 m0, s43, 0x2000
	s_nop 0
	global_load_lds_dwordx4 v[224:225], off
	s_barrier
	s_setprio 1
	s_waitcnt lgkmcnt(3)
	v_mfma_f32_16x16x32_bf16 v[118:121], v[208:211], v[176:179], v[118:121]
	s_waitcnt lgkmcnt(1)
	v_mfma_f32_16x16x32_bf16 v[106:109], v[216:219], v[176:179], v[106:109]
	v_mfma_f32_16x16x32_bf16 v[102:105], v[208:211], v[184:187], v[102:105]
	v_mfma_f32_16x16x32_bf16 v[90:93], v[216:219], v[184:187], v[90:93]
	v_mfma_f32_16x16x32_bf16 v[86:89], v[208:211], v[192:195], v[86:89]
	v_mfma_f32_16x16x32_bf16 v[74:77], v[216:219], v[192:195], v[74:77]
	v_mfma_f32_16x16x32_bf16 v[70:73], v[208:211], v[200:203], v[70:73]
	v_mfma_f32_16x16x32_bf16 v[66:69], v[216:219], v[200:203], v[66:69]
	v_mfma_f32_16x16x32_bf16 v[118:121], v[212:215], v[180:183], v[118:121]
	s_waitcnt lgkmcnt(0)
	v_mfma_f32_16x16x32_bf16 v[106:109], v[234:237], v[180:183], v[106:109]
	v_mfma_f32_16x16x32_bf16 v[102:105], v[212:215], v[188:191], v[102:105]
	v_mfma_f32_16x16x32_bf16 v[90:93], v[234:237], v[188:191], v[90:93]
	v_mfma_f32_16x16x32_bf16 v[86:89], v[212:215], v[196:199], v[86:89]
	v_mfma_f32_16x16x32_bf16 v[74:77], v[234:237], v[196:199], v[74:77]
	v_mfma_f32_16x16x32_bf16 v[70:73], v[212:215], v[204:207], v[70:73]
	v_mfma_f32_16x16x32_bf16 v[66:69], v[234:237], v[204:207], v[66:69]
	s_setprio 0
	s_mov_b32 m0, s36
	v_lshl_add_u64 v[228:229], s[20:21], 0, v[48:49]
	s_barrier
	ds_read_b128 v[176:179], v172 offset:16384
	ds_read_b128 v[180:183], v172 offset:17408
	ds_read_b128 v[184:187], v172 offset:18432
	ds_read_b128 v[188:191], v172 offset:19456
	ds_read_b128 v[192:195], v172 offset:20480
	ds_read_b128 v[196:199], v172 offset:21504
	ds_read_b128 v[200:203], v172 offset:22528
	ds_read_b128 v[204:207], v172 offset:23552
	global_load_lds_dwordx4 v[228:229], off
	v_lshl_add_u64 v[238:239], s[20:21], 0, v[146:147]
	s_mov_b32 m0, s37
	s_nop 0
	global_load_lds_dwordx4 v[238:239], off
	s_barrier
	s_setprio 1
	s_waitcnt lgkmcnt(7)
	v_mfma_f32_16x16x32_bf16 v[62:65], v[130:133], v[176:179], v[62:65]
	v_mfma_f32_16x16x32_bf16 v[58:61], v[138:141], v[176:179], v[58:61]
	s_waitcnt lgkmcnt(5)
	v_mfma_f32_16x16x32_bf16 v[50:53], v[130:133], v[184:187], v[50:53]
	v_mfma_f32_16x16x32_bf16 v[44:47], v[138:141], v[184:187], v[44:47]
	s_waitcnt lgkmcnt(3)
	v_mfma_f32_16x16x32_bf16 v[32:35], v[130:133], v[192:195], v[32:35]
	v_mfma_f32_16x16x32_bf16 v[28:31], v[138:141], v[192:195], v[28:31]
	s_waitcnt lgkmcnt(1)
	v_mfma_f32_16x16x32_bf16 v[16:19], v[130:133], v[200:203], v[16:19]
	v_mfma_f32_16x16x32_bf16 v[12:15], v[138:141], v[200:203], v[12:15]
	v_mfma_f32_16x16x32_bf16 v[62:65], v[134:137], v[180:183], v[62:65]
	v_mfma_f32_16x16x32_bf16 v[58:61], v[142:145], v[180:183], v[58:61]
	v_mfma_f32_16x16x32_bf16 v[50:53], v[134:137], v[188:191], v[50:53]
	v_mfma_f32_16x16x32_bf16 v[44:47], v[142:145], v[188:191], v[44:47]
	v_mfma_f32_16x16x32_bf16 v[32:35], v[134:137], v[196:199], v[32:35]
	v_mfma_f32_16x16x32_bf16 v[28:31], v[142:145], v[196:199], v[28:31]
	s_waitcnt lgkmcnt(0)
	v_mfma_f32_16x16x32_bf16 v[16:19], v[134:137], v[204:207], v[16:19]
	v_mfma_f32_16x16x32_bf16 v[12:15], v[142:145], v[204:207], v[12:15]
	s_setprio 0
	s_barrier
	s_add_u32 s22, s22, s10
	s_addc_u32 s23, s23, 0
	s_add_i32 s43, s44, s35
	v_lshl_add_u64 v[240:241], s[22:23], 0, v[48:49]
	s_mov_b32 m0, s43
	v_lshl_add_u64 v[242:243], s[22:23], 0, v[146:147]
	global_load_lds_dwordx4 v[240:241], off
	s_add_i32 m0, s43, 0x2000
	s_nop 0
	global_load_lds_dwordx4 v[242:243], off
	s_waitcnt vmcnt(6)
	s_barrier
	s_setprio 1
	v_mfma_f32_16x16x32_bf16 v[54:57], v[208:211], v[176:179], v[54:57]
	v_mfma_f32_16x16x32_bf16 v[40:43], v[216:219], v[176:179], v[40:43]
	v_mfma_f32_16x16x32_bf16 v[36:39], v[208:211], v[184:187], v[36:39]
	v_mfma_f32_16x16x32_bf16 v[24:27], v[216:219], v[184:187], v[24:27]
	v_mfma_f32_16x16x32_bf16 v[20:23], v[208:211], v[192:195], v[20:23]
	v_mfma_f32_16x16x32_bf16 v[8:11], v[216:219], v[192:195], v[8:11]
	v_mfma_f32_16x16x32_bf16 v[4:7], v[208:211], v[200:203], v[4:7]
	v_mfma_f32_16x16x32_bf16 v[0:3], v[216:219], v[200:203], v[0:3]
	v_mfma_f32_16x16x32_bf16 v[54:57], v[212:215], v[180:183], v[54:57]
	v_mfma_f32_16x16x32_bf16 v[40:43], v[234:237], v[180:183], v[40:43]
	v_mfma_f32_16x16x32_bf16 v[36:39], v[212:215], v[188:191], v[36:39]
	v_mfma_f32_16x16x32_bf16 v[24:27], v[234:237], v[188:191], v[24:27]
	v_mfma_f32_16x16x32_bf16 v[20:23], v[212:215], v[196:199], v[20:23]
	v_mfma_f32_16x16x32_bf16 v[8:11], v[234:237], v[196:199], v[8:11]
	v_mfma_f32_16x16x32_bf16 v[4:7], v[212:215], v[204:207], v[4:7]
	v_mfma_f32_16x16x32_bf16 v[0:3], v[234:237], v[204:207], v[0:3]
	s_setprio 0
	s_add_i32 s22, 0, 0x18000
	v_add_u32_e32 v142, s22, v170
	s_barrier
	ds_read_b128 v[130:133], v142
	ds_read_b128 v[134:137], v142 offset:1024
	ds_read_b128 v[138:141], v142 offset:2048
	ds_read_b128 v[142:145], v142 offset:3072
	s_add_u32 s20, s20, s10
	s_addc_u32 s21, s21, 0
	s_mov_b32 m0, s38
	v_lshl_add_u64 v[208:209], s[20:21], 0, v[48:49]
	ds_read_b128 v[176:179], v172 offset:32768
	ds_read_b128 v[180:183], v172 offset:33792
	ds_read_b128 v[184:187], v172 offset:34816
	ds_read_b128 v[188:191], v172 offset:35840
	ds_read_b128 v[192:195], v172 offset:36864
	ds_read_b128 v[196:199], v172 offset:37888
	ds_read_b128 v[200:203], v172 offset:38912
	ds_read_b128 v[204:207], v172 offset:39936
	global_load_lds_dwordx4 v[208:209], off
	v_lshl_add_u64 v[208:209], s[20:21], 0, v[146:147]
	s_mov_b32 m0, s39
	s_nop 0
	global_load_lds_dwordx4 v[208:209], off
	s_waitcnt lgkmcnt(8)
	s_barrier
	s_setprio 1
	s_waitcnt lgkmcnt(7)
	v_mfma_f32_16x16x32_bf16 v[126:129], v[130:133], v[176:179], v[126:129]
	v_mfma_f32_16x16x32_bf16 v[122:125], v[138:141], v[176:179], v[122:125]
	s_waitcnt lgkmcnt(5)
	v_mfma_f32_16x16x32_bf16 v[114:117], v[130:133], v[184:187], v[114:117]
	v_mfma_f32_16x16x32_bf16 v[110:113], v[138:141], v[184:187], v[110:113]
	s_waitcnt lgkmcnt(3)
	v_mfma_f32_16x16x32_bf16 v[98:101], v[130:133], v[192:195], v[98:101]
	v_mfma_f32_16x16x32_bf16 v[94:97], v[138:141], v[192:195], v[94:97]
	s_waitcnt lgkmcnt(1)
	v_mfma_f32_16x16x32_bf16 v[82:85], v[130:133], v[200:203], v[82:85]
	v_mfma_f32_16x16x32_bf16 v[78:81], v[138:141], v[200:203], v[78:81]
	v_mfma_f32_16x16x32_bf16 v[126:129], v[134:137], v[180:183], v[126:129]
	v_mfma_f32_16x16x32_bf16 v[122:125], v[142:145], v[180:183], v[122:125]
	v_mfma_f32_16x16x32_bf16 v[114:117], v[134:137], v[188:191], v[114:117]
	v_mfma_f32_16x16x32_bf16 v[110:113], v[142:145], v[188:191], v[110:113]
	v_mfma_f32_16x16x32_bf16 v[98:101], v[134:137], v[196:199], v[98:101]
	v_mfma_f32_16x16x32_bf16 v[94:97], v[142:145], v[196:199], v[94:97]
	s_waitcnt lgkmcnt(0)
	v_mfma_f32_16x16x32_bf16 v[82:85], v[134:137], v[204:207], v[82:85]
	v_mfma_f32_16x16x32_bf16 v[78:81], v[142:145], v[204:207], v[78:81]
	s_setprio 0
	s_barrier
	s_add_i32 s20, 0, 0x1c000
	s_add_i32 s21, s22, s35
	v_add_u32_e32 v173, s20, v170
	v_lshl_add_u64 v[168:169], v[168:169], 0, s[0:1]
	s_mov_b32 m0, s21
	ds_read_b128 v[208:211], v173
	ds_read_b128 v[212:215], v173 offset:1024
	ds_read_b128 v[216:219], v173 offset:2048
	ds_read_b128 v[234:237], v173 offset:3072
	global_load_lds_dwordx4 v[168:169], off
	v_lshl_add_u64 v[168:169], v[224:225], 0, s[0:1]
	s_add_i32 m0, s21, 0x2000
	s_nop 0
	global_load_lds_dwordx4 v[168:169], off
	s_barrier
	s_setprio 1
	s_waitcnt lgkmcnt(3)
	v_mfma_f32_16x16x32_bf16 v[118:121], v[208:211], v[176:179], v[118:121]
	s_waitcnt lgkmcnt(1)
	v_mfma_f32_16x16x32_bf16 v[106:109], v[216:219], v[176:179], v[106:109]
	v_mfma_f32_16x16x32_bf16 v[102:105], v[208:211], v[184:187], v[102:105]
	v_mfma_f32_16x16x32_bf16 v[90:93], v[216:219], v[184:187], v[90:93]
	v_mfma_f32_16x16x32_bf16 v[86:89], v[208:211], v[192:195], v[86:89]
	v_mfma_f32_16x16x32_bf16 v[74:77], v[216:219], v[192:195], v[74:77]
	v_mfma_f32_16x16x32_bf16 v[70:73], v[208:211], v[200:203], v[70:73]
	v_mfma_f32_16x16x32_bf16 v[66:69], v[216:219], v[200:203], v[66:69]
	v_mfma_f32_16x16x32_bf16 v[118:121], v[212:215], v[180:183], v[118:121]
	s_waitcnt lgkmcnt(0)
	v_mfma_f32_16x16x32_bf16 v[106:109], v[234:237], v[180:183], v[106:109]
	v_mfma_f32_16x16x32_bf16 v[102:105], v[212:215], v[188:191], v[102:105]
	v_mfma_f32_16x16x32_bf16 v[90:93], v[234:237], v[188:191], v[90:93]
	v_mfma_f32_16x16x32_bf16 v[86:89], v[212:215], v[196:199], v[86:89]
	v_mfma_f32_16x16x32_bf16 v[74:77], v[234:237], v[196:199], v[74:77]
	v_mfma_f32_16x16x32_bf16 v[70:73], v[212:215], v[204:207], v[70:73]
	v_mfma_f32_16x16x32_bf16 v[66:69], v[234:237], v[204:207], v[66:69]
	s_setprio 0
	s_mov_b32 m0, s64
	v_lshl_add_u64 v[168:169], v[228:229], 0, s[0:1]
	s_barrier
	ds_read_b128 v[176:179], v172 offset:49152
	ds_read_b128 v[180:183], v172 offset:50176
	ds_read_b128 v[184:187], v172 offset:51200
	ds_read_b128 v[188:191], v172 offset:52224
	ds_read_b128 v[192:195], v172 offset:53248
	ds_read_b128 v[196:199], v172 offset:54272
	ds_read_b128 v[200:203], v172 offset:55296
	ds_read_b128 v[204:207], v172 offset:56320
	global_load_lds_dwordx4 v[168:169], off
	v_lshl_add_u64 v[168:169], v[238:239], 0, s[0:1]
	s_mov_b32 m0, s65
	s_nop 0
	global_load_lds_dwordx4 v[168:169], off
	s_barrier
	s_setprio 1
	s_waitcnt lgkmcnt(7)
	v_mfma_f32_16x16x32_bf16 v[62:65], v[130:133], v[176:179], v[62:65]
	v_mfma_f32_16x16x32_bf16 v[58:61], v[138:141], v[176:179], v[58:61]
	s_waitcnt lgkmcnt(5)
	v_mfma_f32_16x16x32_bf16 v[50:53], v[130:133], v[184:187], v[50:53]
	v_mfma_f32_16x16x32_bf16 v[44:47], v[138:141], v[184:187], v[44:47]
	s_waitcnt lgkmcnt(3)
	v_mfma_f32_16x16x32_bf16 v[32:35], v[130:133], v[192:195], v[32:35]
	v_mfma_f32_16x16x32_bf16 v[28:31], v[138:141], v[192:195], v[28:31]
	s_waitcnt lgkmcnt(1)
	v_mfma_f32_16x16x32_bf16 v[16:19], v[130:133], v[200:203], v[16:19]
	v_mfma_f32_16x16x32_bf16 v[12:15], v[138:141], v[200:203], v[12:15]
	v_mfma_f32_16x16x32_bf16 v[62:65], v[134:137], v[180:183], v[62:65]
	v_mfma_f32_16x16x32_bf16 v[58:61], v[142:145], v[180:183], v[58:61]
	v_mfma_f32_16x16x32_bf16 v[50:53], v[134:137], v[188:191], v[50:53]
	v_mfma_f32_16x16x32_bf16 v[44:47], v[142:145], v[188:191], v[44:47]
	v_mfma_f32_16x16x32_bf16 v[32:35], v[134:137], v[196:199], v[32:35]
	v_mfma_f32_16x16x32_bf16 v[28:31], v[142:145], v[196:199], v[28:31]
	s_waitcnt lgkmcnt(0)
	v_mfma_f32_16x16x32_bf16 v[16:19], v[134:137], v[204:207], v[16:19]
	v_mfma_f32_16x16x32_bf16 v[12:15], v[142:145], v[204:207], v[12:15]
	s_setprio 0
	s_barrier
	s_add_i32 s20, s20, s35
	v_lshl_add_u64 v[130:131], v[240:241], 0, s[0:1]
	s_mov_b32 m0, s20
	s_nop 0
	global_load_lds_dwordx4 v[130:131], off
	v_lshl_add_u64 v[130:131], v[242:243], 0, s[0:1]
	s_add_i32 m0, s20, 0x2000
	s_nop 0
	global_load_lds_dwordx4 v[130:131], off
	s_waitcnt vmcnt(6)
	s_barrier
	s_setprio 1
	v_mfma_f32_16x16x32_bf16 v[54:57], v[208:211], v[176:179], v[54:57]
	v_mfma_f32_16x16x32_bf16 v[40:43], v[216:219], v[176:179], v[40:43]
	v_mfma_f32_16x16x32_bf16 v[36:39], v[208:211], v[184:187], v[36:39]
	v_mfma_f32_16x16x32_bf16 v[24:27], v[216:219], v[184:187], v[24:27]
	v_mfma_f32_16x16x32_bf16 v[20:23], v[208:211], v[192:195], v[20:23]
	v_mfma_f32_16x16x32_bf16 v[8:11], v[216:219], v[192:195], v[8:11]
	v_mfma_f32_16x16x32_bf16 v[4:7], v[208:211], v[200:203], v[4:7]
	v_mfma_f32_16x16x32_bf16 v[0:3], v[216:219], v[200:203], v[0:3]
	v_mfma_f32_16x16x32_bf16 v[54:57], v[212:215], v[180:183], v[54:57]
	v_mfma_f32_16x16x32_bf16 v[40:43], v[234:237], v[180:183], v[40:43]
	v_mfma_f32_16x16x32_bf16 v[36:39], v[212:215], v[188:191], v[36:39]
	v_mfma_f32_16x16x32_bf16 v[24:27], v[234:237], v[188:191], v[24:27]
	v_mfma_f32_16x16x32_bf16 v[20:23], v[212:215], v[196:199], v[20:23]
	v_mfma_f32_16x16x32_bf16 v[8:11], v[234:237], v[196:199], v[8:11]
	v_mfma_f32_16x16x32_bf16 v[4:7], v[212:215], v[204:207], v[4:7]
	v_mfma_f32_16x16x32_bf16 v[0:3], v[234:237], v[204:207], v[0:3]
	s_setprio 0
	s_add_u32 s16, s16, 0x100
	s_addc_u32 s17, s17, 0
	s_add_u32 s24, s24, 0x100
	s_addc_u32 s25, s25, 0
	s_cmp_ge_u32 s42, s54
	s_mov_b32 s20, s42
	s_barrier
	s_cbranch_scc0 .LBB0_268
	s_lshl_b32 s22, s69, 8
	s_cmpk_gt_i32 s69, 0x7f
	s_mov_b64 s[20:21], -1
	s_cbranch_scc0 .LBB0_271
	s_mov_b32 s17, s73
	s_add_i32 s16, s22, 0xffff8000
	s_lshl_b64 s[16:17], s[16:17], 12
	s_add_u32 s16, s55, s16
	s_addc_u32 s17, s56, s17
	s_mov_b64 s[20:21], 0

.LBB0_288:
	s_add_i32 s41, s22, 2
	s_add_u32 s24, s20, 0x80
	s_addc_u32 s23, s21, 0
	s_add_i32 s63, 0, 0x10000
	v_add_u32_e32 v155, s63, v152
	ds_read_b128 v[156:159], v155
	ds_read_b128 v[160:163], v155 offset:1024
	ds_read_b128 v[164:167], v155 offset:2048
	ds_read_b128 v[168:171], v155 offset:3072
	s_cmp_eq_u32 s55, s22
	s_cselect_b32 s22, s12, s24
	s_cselect_b32 s23, s13, s23
	s_cselect_b32 s25, s17, s40
	s_cselect_b32 s24, s16, s3
	v_lshl_add_u64 v[172:173], s[20:21], 0, v[148:149]
	s_add_i32 m0, s43, 0xc000
	ds_read_b128 v[176:179], v154
	ds_read_b128 v[180:183], v154 offset:1024
	ds_read_b128 v[184:187], v154 offset:2048
	ds_read_b128 v[188:191], v154 offset:3072
	ds_read_b128 v[192:195], v154 offset:4096
	ds_read_b128 v[196:199], v154 offset:5120
	ds_read_b128 v[200:203], v154 offset:6144
	ds_read_b128 v[204:207], v154 offset:7168
	global_load_lds_dwordx4 v[172:173], off
	v_lshl_add_u64 v[172:173], s[20:21], 0, v[150:151]
	s_add_i32 m0, s43, 0xe000
	s_nop 0
	global_load_lds_dwordx4 v[172:173], off
	s_waitcnt lgkmcnt(8)
	s_barrier
	s_setprio 1
	s_waitcnt lgkmcnt(7)
	v_mfma_f32_16x16x32_bf16 v[126:129], v[156:159], v[176:179], v[126:129]
	v_mfma_f32_16x16x32_bf16 v[122:125], v[164:167], v[176:179], v[122:125]
	s_waitcnt lgkmcnt(5)
	v_mfma_f32_16x16x32_bf16 v[118:121], v[156:159], v[184:187], v[118:121]
	v_mfma_f32_16x16x32_bf16 v[114:117], v[164:167], v[184:187], v[114:117]
	s_waitcnt lgkmcnt(3)
	v_mfma_f32_16x16x32_bf16 v[110:113], v[156:159], v[192:195], v[110:113]
	v_mfma_f32_16x16x32_bf16 v[106:109], v[164:167], v[192:195], v[106:109]
	s_waitcnt lgkmcnt(1)
	v_mfma_f32_16x16x32_bf16 v[98:101], v[156:159], v[200:203], v[98:101]
	v_mfma_f32_16x16x32_bf16 v[90:93], v[164:167], v[200:203], v[90:93]
	v_mfma_f32_16x16x32_bf16 v[126:129], v[160:163], v[180:183], v[126:129]
	v_mfma_f32_16x16x32_bf16 v[122:125], v[168:171], v[180:183], v[122:125]
	v_mfma_f32_16x16x32_bf16 v[118:121], v[160:163], v[188:191], v[118:121]
	v_mfma_f32_16x16x32_bf16 v[114:117], v[168:171], v[188:191], v[114:117]
	v_mfma_f32_16x16x32_bf16 v[110:113], v[160:163], v[196:199], v[110:113]
	v_mfma_f32_16x16x32_bf16 v[106:109], v[168:171], v[196:199], v[106:109]
	s_waitcnt lgkmcnt(0)
	v_mfma_f32_16x16x32_bf16 v[98:101], v[160:163], v[204:207], v[98:101]
	v_mfma_f32_16x16x32_bf16 v[90:93], v[168:171], v[204:207], v[90:93]
	s_setprio 0
	s_barrier
	s_add_i32 s64, 0, 0x14000
	s_add_i32 s63, s63, s37
	v_add_u32_e32 v155, s64, v152
	v_lshl_add_u64 v[172:173], s[24:25], 0, v[48:49]
	s_mov_b32 m0, s63
	ds_read_b128 v[208:211], v155
	ds_read_b128 v[212:215], v155 offset:1024
	ds_read_b128 v[216:219], v155 offset:2048
	ds_read_b128 v[234:237], v155 offset:3072
	global_load_lds_dwordx4 v[172:173], off
	v_lshl_add_u64 v[224:225], s[24:25], 0, v[130:131]
	s_add_i32 m0, s63, 0x2000
	s_nop 0
	global_load_lds_dwordx4 v[224:225], off
	s_barrier
	s_setprio 1
	s_waitcnt lgkmcnt(3)
	v_mfma_f32_16x16x32_bf16 v[102:105], v[208:211], v[176:179], v[102:105]
	s_waitcnt lgkmcnt(1)
	v_mfma_f32_16x16x32_bf16 v[94:97], v[216:219], v[176:179], v[94:97]
	v_mfma_f32_16x16x32_bf16 v[86:89], v[208:211], v[184:187], v[86:89]
	v_mfma_f32_16x16x32_bf16 v[82:85], v[216:219], v[184:187], v[82:85]
	v_mfma_f32_16x16x32_bf16 v[78:81], v[208:211], v[192:195], v[78:81]
	v_mfma_f32_16x16x32_bf16 v[74:77], v[216:219], v[192:195], v[74:77]
	v_mfma_f32_16x16x32_bf16 v[70:73], v[208:211], v[200:203], v[70:73]
	v_mfma_f32_16x16x32_bf16 v[66:69], v[216:219], v[200:203], v[66:69]
	v_mfma_f32_16x16x32_bf16 v[102:105], v[212:215], v[180:183], v[102:105]
	s_waitcnt lgkmcnt(0)
	v_mfma_f32_16x16x32_bf16 v[94:97], v[234:237], v[180:183], v[94:97]
	v_mfma_f32_16x16x32_bf16 v[86:89], v[212:215], v[188:191], v[86:89]
	v_mfma_f32_16x16x32_bf16 v[82:85], v[234:237], v[188:191], v[82:85]
	v_mfma_f32_16x16x32_bf16 v[78:81], v[212:215], v[196:199], v[78:81]
	v_mfma_f32_16x16x32_bf16 v[74:77], v[234:237], v[196:199], v[74:77]
	v_mfma_f32_16x16x32_bf16 v[70:73], v[212:215], v[204:207], v[70:73]
	v_mfma_f32_16x16x32_bf16 v[66:69], v[234:237], v[204:207], v[66:69]
	s_setprio 0
	s_mov_b32 m0, s43
	v_lshl_add_u64 v[228:229], s[22:23], 0, v[48:49]
	s_barrier
	ds_read_b128 v[176:179], v154 offset:16384
	ds_read_b128 v[180:183], v154 offset:17408
	ds_read_b128 v[184:187], v154 offset:18432
	ds_read_b128 v[188:191], v154 offset:19456
	ds_read_b128 v[192:195], v154 offset:20480
	ds_read_b128 v[196:199], v154 offset:21504
	ds_read_b128 v[200:203], v154 offset:22528
	ds_read_b128 v[204:207], v154 offset:23552
	global_load_lds_dwordx4 v[228:229], off
	v_lshl_add_u64 v[238:239], s[22:23], 0, v[130:131]
	s_mov_b32 m0, s44
	s_nop 0
	global_load_lds_dwordx4 v[238:239], off
	s_barrier
	s_setprio 1
	s_waitcnt lgkmcnt(7)
	v_mfma_f32_16x16x32_bf16 v[62:65], v[156:159], v[176:179], v[62:65]
	v_mfma_f32_16x16x32_bf16 v[58:61], v[164:167], v[176:179], v[58:61]
	s_waitcnt lgkmcnt(5)
	v_mfma_f32_16x16x32_bf16 v[54:57], v[156:159], v[184:187], v[54:57]
	v_mfma_f32_16x16x32_bf16 v[50:53], v[164:167], v[184:187], v[50:53]
	s_waitcnt lgkmcnt(3)
	v_mfma_f32_16x16x32_bf16 v[44:47], v[156:159], v[192:195], v[44:47]
	v_mfma_f32_16x16x32_bf16 v[40:43], v[164:167], v[192:195], v[40:43]
	s_waitcnt lgkmcnt(1)
	v_mfma_f32_16x16x32_bf16 v[32:35], v[156:159], v[200:203], v[32:35]
	v_mfma_f32_16x16x32_bf16 v[24:27], v[164:167], v[200:203], v[24:27]
	v_mfma_f32_16x16x32_bf16 v[62:65], v[160:163], v[180:183], v[62:65]
	v_mfma_f32_16x16x32_bf16 v[58:61], v[168:171], v[180:183], v[58:61]
	v_mfma_f32_16x16x32_bf16 v[54:57], v[160:163], v[188:191], v[54:57]
	v_mfma_f32_16x16x32_bf16 v[50:53], v[168:171], v[188:191], v[50:53]
	v_mfma_f32_16x16x32_bf16 v[44:47], v[160:163], v[196:199], v[44:47]
	v_mfma_f32_16x16x32_bf16 v[40:43], v[168:171], v[196:199], v[40:43]
	s_waitcnt lgkmcnt(0)
	v_mfma_f32_16x16x32_bf16 v[32:35], v[160:163], v[204:207], v[32:35]
	v_mfma_f32_16x16x32_bf16 v[24:27], v[168:171], v[204:207], v[24:27]
	s_setprio 0
	s_barrier
	s_add_u32 s24, s24, s10
	s_addc_u32 s25, s25, 0
	s_add_i32 s63, s64, s37
	v_lshl_add_u64 v[240:241], s[24:25], 0, v[48:49]
	s_mov_b32 m0, s63
	v_lshl_add_u64 v[242:243], s[24:25], 0, v[130:131]
	global_load_lds_dwordx4 v[240:241], off
	s_add_i32 m0, s63, 0x2000
	s_nop 0
	global_load_lds_dwordx4 v[242:243], off
	s_waitcnt vmcnt(6)
	s_barrier
	s_setprio 1
	v_mfma_f32_16x16x32_bf16 v[36:39], v[208:211], v[176:179], v[36:39]
	v_mfma_f32_16x16x32_bf16 v[28:31], v[216:219], v[176:179], v[28:31]
	v_mfma_f32_16x16x32_bf16 v[20:23], v[208:211], v[184:187], v[20:23]
	v_mfma_f32_16x16x32_bf16 v[16:19], v[216:219], v[184:187], v[16:19]
	v_mfma_f32_16x16x32_bf16 v[12:15], v[208:211], v[192:195], v[12:15]
	v_mfma_f32_16x16x32_bf16 v[8:11], v[216:219], v[192:195], v[8:11]
	v_mfma_f32_16x16x32_bf16 v[4:7], v[208:211], v[200:203], v[4:7]
	v_mfma_f32_16x16x32_bf16 v[0:3], v[216:219], v[200:203], v[0:3]
	v_mfma_f32_16x16x32_bf16 v[36:39], v[212:215], v[180:183], v[36:39]
	v_mfma_f32_16x16x32_bf16 v[28:31], v[234:237], v[180:183], v[28:31]
	v_mfma_f32_16x16x32_bf16 v[20:23], v[212:215], v[188:191], v[20:23]
	v_mfma_f32_16x16x32_bf16 v[16:19], v[234:237], v[188:191], v[16:19]
	v_mfma_f32_16x16x32_bf16 v[12:15], v[212:215], v[196:199], v[12:15]
	v_mfma_f32_16x16x32_bf16 v[8:11], v[234:237], v[196:199], v[8:11]
	v_mfma_f32_16x16x32_bf16 v[4:7], v[212:215], v[204:207], v[4:7]
	v_mfma_f32_16x16x32_bf16 v[0:3], v[234:237], v[204:207], v[0:3]
	s_setprio 0
	s_add_i32 s24, 0, 0x18000
	v_add_u32_e32 v155, s24, v152
	s_barrier
	ds_read_b128 v[156:159], v155
	ds_read_b128 v[160:163], v155 offset:1024
	ds_read_b128 v[164:167], v155 offset:2048
	ds_read_b128 v[168:171], v155 offset:3072
	s_add_u32 s22, s22, s10
	s_addc_u32 s23, s23, 0
	s_mov_b32 m0, s46
	v_lshl_add_u64 v[208:209], s[22:23], 0, v[48:49]
	ds_read_b128 v[176:179], v154 offset:32768
	ds_read_b128 v[180:183], v154 offset:33792
	ds_read_b128 v[184:187], v154 offset:34816
	ds_read_b128 v[188:191], v154 offset:35840
	ds_read_b128 v[192:195], v154 offset:36864
	ds_read_b128 v[196:199], v154 offset:37888
	ds_read_b128 v[200:203], v154 offset:38912
	ds_read_b128 v[204:207], v154 offset:39936
	global_load_lds_dwordx4 v[208:209], off
	v_lshl_add_u64 v[208:209], s[22:23], 0, v[130:131]
	s_mov_b32 m0, s47
	s_nop 0
	global_load_lds_dwordx4 v[208:209], off
	s_waitcnt lgkmcnt(8)
	s_barrier
	s_setprio 1
	s_waitcnt lgkmcnt(7)
	v_mfma_f32_16x16x32_bf16 v[126:129], v[156:159], v[176:179], v[126:129]
	v_mfma_f32_16x16x32_bf16 v[122:125], v[164:167], v[176:179], v[122:125]
	s_waitcnt lgkmcnt(5)
	v_mfma_f32_16x16x32_bf16 v[118:121], v[156:159], v[184:187], v[118:121]
	v_mfma_f32_16x16x32_bf16 v[114:117], v[164:167], v[184:187], v[114:117]
	s_waitcnt lgkmcnt(3)
	v_mfma_f32_16x16x32_bf16 v[110:113], v[156:159], v[192:195], v[110:113]
	v_mfma_f32_16x16x32_bf16 v[106:109], v[164:167], v[192:195], v[106:109]
	s_waitcnt lgkmcnt(1)
	v_mfma_f32_16x16x32_bf16 v[98:101], v[156:159], v[200:203], v[98:101]
	v_mfma_f32_16x16x32_bf16 v[90:93], v[164:167], v[200:203], v[90:93]
	v_mfma_f32_16x16x32_bf16 v[126:129], v[160:163], v[180:183], v[126:129]
	v_mfma_f32_16x16x32_bf16 v[122:125], v[168:171], v[180:183], v[122:125]
	v_mfma_f32_16x16x32_bf16 v[118:121], v[160:163], v[188:191], v[118:121]
	v_mfma_f32_16x16x32_bf16 v[114:117], v[168:171], v[188:191], v[114:117]
	v_mfma_f32_16x16x32_bf16 v[110:113], v[160:163], v[196:199], v[110:113]
	v_mfma_f32_16x16x32_bf16 v[106:109], v[168:171], v[196:199], v[106:109]
	s_waitcnt lgkmcnt(0)
	v_mfma_f32_16x16x32_bf16 v[98:101], v[160:163], v[204:207], v[98:101]
	v_mfma_f32_16x16x32_bf16 v[90:93], v[168:171], v[204:207], v[90:93]
	s_setprio 0
	s_barrier
	s_add_i32 s22, 0, 0x1c000
	s_add_i32 s23, s24, s37
	v_add_u32_e32 v155, s22, v152
	v_lshl_add_u64 v[172:173], v[172:173], 0, s[0:1]
	s_mov_b32 m0, s23
	ds_read_b128 v[208:211], v155
	ds_read_b128 v[212:215], v155 offset:1024
	ds_read_b128 v[216:219], v155 offset:2048
	ds_read_b128 v[234:237], v155 offset:3072
	global_load_lds_dwordx4 v[172:173], off
	v_lshl_add_u64 v[172:173], v[224:225], 0, s[0:1]
	s_add_i32 m0, s23, 0x2000
	s_nop 0
	global_load_lds_dwordx4 v[172:173], off
	s_barrier
	s_setprio 1
	s_waitcnt lgkmcnt(3)
	v_mfma_f32_16x16x32_bf16 v[102:105], v[208:211], v[176:179], v[102:105]
	s_waitcnt lgkmcnt(1)
	v_mfma_f32_16x16x32_bf16 v[94:97], v[216:219], v[176:179], v[94:97]
	v_mfma_f32_16x16x32_bf16 v[86:89], v[208:211], v[184:187], v[86:89]
	v_mfma_f32_16x16x32_bf16 v[82:85], v[216:219], v[184:187], v[82:85]
	v_mfma_f32_16x16x32_bf16 v[78:81], v[208:211], v[192:195], v[78:81]
	v_mfma_f32_16x16x32_bf16 v[74:77], v[216:219], v[192:195], v[74:77]
	v_mfma_f32_16x16x32_bf16 v[70:73], v[208:211], v[200:203], v[70:73]
	v_mfma_f32_16x16x32_bf16 v[66:69], v[216:219], v[200:203], v[66:69]
	v_mfma_f32_16x16x32_bf16 v[102:105], v[212:215], v[180:183], v[102:105]
	s_waitcnt lgkmcnt(0)
	v_mfma_f32_16x16x32_bf16 v[94:97], v[234:237], v[180:183], v[94:97]
	v_mfma_f32_16x16x32_bf16 v[86:89], v[212:215], v[188:191], v[86:89]
	v_mfma_f32_16x16x32_bf16 v[82:85], v[234:237], v[188:191], v[82:85]
	v_mfma_f32_16x16x32_bf16 v[78:81], v[212:215], v[196:199], v[78:81]
	v_mfma_f32_16x16x32_bf16 v[74:77], v[234:237], v[196:199], v[74:77]
	v_mfma_f32_16x16x32_bf16 v[70:73], v[212:215], v[204:207], v[70:73]
	v_mfma_f32_16x16x32_bf16 v[66:69], v[234:237], v[204:207], v[66:69]
	s_setprio 0
	s_mov_b32 m0, s50
	v_lshl_add_u64 v[172:173], v[228:229], 0, s[0:1]
	s_barrier
	ds_read_b128 v[176:179], v154 offset:49152
	ds_read_b128 v[180:183], v154 offset:50176
	ds_read_b128 v[184:187], v154 offset:51200
	ds_read_b128 v[188:191], v154 offset:52224
	ds_read_b128 v[192:195], v154 offset:53248
	ds_read_b128 v[196:199], v154 offset:54272
	ds_read_b128 v[200:203], v154 offset:55296
	ds_read_b128 v[204:207], v154 offset:56320
	global_load_lds_dwordx4 v[172:173], off
	v_lshl_add_u64 v[172:173], v[238:239], 0, s[0:1]
	s_mov_b32 m0, s51
	s_nop 0
	global_load_lds_dwordx4 v[172:173], off
	s_barrier
	s_setprio 1
	s_waitcnt lgkmcnt(7)
	v_mfma_f32_16x16x32_bf16 v[62:65], v[156:159], v[176:179], v[62:65]
	v_mfma_f32_16x16x32_bf16 v[58:61], v[164:167], v[176:179], v[58:61]
	s_waitcnt lgkmcnt(5)
	v_mfma_f32_16x16x32_bf16 v[54:57], v[156:159], v[184:187], v[54:57]
	v_mfma_f32_16x16x32_bf16 v[50:53], v[164:167], v[184:187], v[50:53]
	s_waitcnt lgkmcnt(3)
	v_mfma_f32_16x16x32_bf16 v[44:47], v[156:159], v[192:195], v[44:47]
	v_mfma_f32_16x16x32_bf16 v[40:43], v[164:167], v[192:195], v[40:43]
	s_waitcnt lgkmcnt(1)
	v_mfma_f32_16x16x32_bf16 v[32:35], v[156:159], v[200:203], v[32:35]
	v_mfma_f32_16x16x32_bf16 v[24:27], v[164:167], v[200:203], v[24:27]
	v_mfma_f32_16x16x32_bf16 v[62:65], v[160:163], v[180:183], v[62:65]
	v_mfma_f32_16x16x32_bf16 v[58:61], v[168:171], v[180:183], v[58:61]
	v_mfma_f32_16x16x32_bf16 v[54:57], v[160:163], v[188:191], v[54:57]
	v_mfma_f32_16x16x32_bf16 v[50:53], v[168:171], v[188:191], v[50:53]
	v_mfma_f32_16x16x32_bf16 v[44:47], v[160:163], v[196:199], v[44:47]
	v_mfma_f32_16x16x32_bf16 v[40:43], v[168:171], v[196:199], v[40:43]
	s_waitcnt lgkmcnt(0)
	v_mfma_f32_16x16x32_bf16 v[32:35], v[160:163], v[204:207], v[32:35]
	v_mfma_f32_16x16x32_bf16 v[24:27], v[168:171], v[204:207], v[24:27]
	s_setprio 0
	s_barrier
	s_add_i32 s22, s22, s37
	v_lshl_add_u64 v[156:157], v[240:241], 0, s[0:1]
	s_mov_b32 m0, s22
	s_nop 0
	global_load_lds_dwordx4 v[156:157], off
	v_lshl_add_u64 v[156:157], v[242:243], 0, s[0:1]
	s_add_i32 m0, s22, 0x2000
	s_nop 0
	global_load_lds_dwordx4 v[156:157], off
	s_waitcnt vmcnt(6)
	s_barrier
	s_setprio 1
	v_mfma_f32_16x16x32_bf16 v[36:39], v[208:211], v[176:179], v[36:39]
	v_mfma_f32_16x16x32_bf16 v[28:31], v[216:219], v[176:179], v[28:31]
	v_mfma_f32_16x16x32_bf16 v[20:23], v[208:211], v[184:187], v[20:23]
	v_mfma_f32_16x16x32_bf16 v[16:19], v[216:219], v[184:187], v[16:19]
	v_mfma_f32_16x16x32_bf16 v[12:15], v[208:211], v[192:195], v[12:15]
	v_mfma_f32_16x16x32_bf16 v[8:11], v[216:219], v[192:195], v[8:11]
	v_mfma_f32_16x16x32_bf16 v[4:7], v[208:211], v[200:203], v[4:7]
	v_mfma_f32_16x16x32_bf16 v[0:3], v[216:219], v[200:203], v[0:3]
	v_mfma_f32_16x16x32_bf16 v[36:39], v[212:215], v[180:183], v[36:39]
	v_mfma_f32_16x16x32_bf16 v[28:31], v[234:237], v[180:183], v[28:31]
	v_mfma_f32_16x16x32_bf16 v[20:23], v[212:215], v[188:191], v[20:23]
	v_mfma_f32_16x16x32_bf16 v[16:19], v[234:237], v[188:191], v[16:19]
	v_mfma_f32_16x16x32_bf16 v[12:15], v[212:215], v[196:199], v[12:15]
	v_mfma_f32_16x16x32_bf16 v[8:11], v[234:237], v[196:199], v[8:11]
	v_mfma_f32_16x16x32_bf16 v[4:7], v[212:215], v[204:207], v[4:7]
	v_mfma_f32_16x16x32_bf16 v[0:3], v[234:237], v[204:207], v[0:3]
	s_setprio 0
	s_add_u32 s20, s20, 0x100
	s_addc_u32 s21, s21, 0
	s_add_u32 s3, s3, 0x100
	s_addc_u32 s40, s40, 0
	s_cmp_ge_u32 s41, s54
	s_mov_b32 s22, s41
	s_barrier
	s_cbranch_scc0 .LBB0_288
	s_lshl_b32 s20, s45, 8
	s_ashr_i32 s3, s2, 31
	s_ashr_i32 s21, s20, 31
	s_lshl_b64 s[20:21], s[20:21], 12
	s_lshl_b64 s[2:3], s[2:3], 23
	s_add_u32 s2, s48, s2
	s_addc_u32 s3, s49, s3
	s_add_u32 s2, s2, s20
	v_lshl_or_b32 v156, s42, 8, v153
	s_addc_u32 s3, s3, s21
	v_ashrrev_i32_e32 v157, 31, v156
	v_lshl_add_u64 v[156:157], v[156:157], 2, s[2:3]
	s_brev_b32 s2, 31
	s_mov_b32 s3, -1
	v_lshl_add_u64 v[156:157], v[156:157], 0, s[2:3]
	v_lshl_add_u64 v[158:159], v[156:157], 0, v[132:133]
	global_store_dwordx4 v[158:159], v[126:129], off
	global_store_dwordx4 v[158:159], v[122:125], off offset:64
	global_store_dwordx4 v[158:159], v[102:105], off offset:512
	global_store_dwordx4 v[158:159], v[94:97], off offset:576
	s_and_b64 vcc, exec, s[6:7]
	s_mov_b32 s2, s56
	v_lshl_add_u64 v[94:95], v[156:157], 0, v[134:135]
	global_store_dwordx4 v[94:95], v[118:121], off
	global_store_dwordx4 v[94:95], v[114:117], off offset:64
	global_store_dwordx4 v[94:95], v[86:89], off offset:512
	global_store_dwordx4 v[94:95], v[82:85], off offset:576
	s_mov_b32 s42, s57
	s_mov_b32 s45, s59
	v_lshl_add_u64 v[82:83], v[156:157], 0, v[136:137]
	global_store_dwordx4 v[82:83], v[110:113], off
	global_store_dwordx4 v[82:83], v[106:109], off offset:64
	global_store_dwordx4 v[82:83], v[78:81], off offset:512
	global_store_dwordx4 v[82:83], v[74:77], off offset:576
	s_mov_b64 s[22:23], s[16:17]
	s_mov_b64 s[20:21], s[12:13]
	v_lshl_add_u64 v[74:75], v[156:157], 0, v[138:139]
	global_store_dwordx4 v[74:75], v[98:101], off
	global_store_dwordx4 v[74:75], v[90:93], off offset:64
	global_store_dwordx4 v[74:75], v[70:73], off offset:512
	global_store_dwordx4 v[74:75], v[66:69], off offset:576
	s_nop 1
	v_lshl_add_u64 v[66:67], v[156:157], 0, v[140:141]
	global_store_dwordx4 v[66:67], v[62:65], off
	global_store_dwordx4 v[66:67], v[58:61], off offset:64
	global_store_dwordx4 v[66:67], v[36:39], off offset:512
	global_store_dwordx4 v[66:67], v[28:31], off offset:576
	s_nop 1
	v_lshl_add_u64 v[28:29], v[156:157], 0, v[142:143]
	global_store_dwordx4 v[28:29], v[54:57], off
	global_store_dwordx4 v[28:29], v[50:53], off offset:64
	global_store_dwordx4 v[28:29], v[20:23], off offset:512
	global_store_dwordx4 v[28:29], v[16:19], off offset:576
	s_nop 1
	v_lshl_add_u64 v[16:17], v[156:157], 0, v[144:145]
	global_store_dwordx4 v[16:17], v[44:47], off
	global_store_dwordx4 v[16:17], v[40:43], off offset:64
	global_store_dwordx4 v[16:17], v[12:15], off offset:512
	global_store_dwordx4 v[16:17], v[8:11], off offset:576
	s_nop 1
	v_lshl_add_u64 v[8:9], v[156:157], 0, v[146:147]
	global_store_dwordx4 v[8:9], v[32:35], off
	global_store_dwordx4 v[8:9], v[24:27], off offset:64
	global_store_dwordx4 v[8:9], v[4:7], off offset:512
	global_store_dwordx4 v[8:9], v[0:3], off offset:576
	s_cbranch_vccz .LBB0_281
	s_waitcnt vmcnt(0)
	v_readlane_b32 s46, v254, 33
	v_readlane_b32 s48, v254, 35
	s_cmpk_gt_u32 s34, 0xff
	v_readlane_b32 s54, v254, 31
	v_readlane_b32 s47, v254, 34
	v_readlane_b32 s49, v254, 36
	v_readlane_b32 s55, v254, 39
	s_mov_b32 s57, s65
	s_cbranch_scc1 .LBB0_292
	s_barrier

.LBB0_320:
	s_add_u32 s34, s30, 0xfffc0080
	s_addc_u32 s35, s31, -1
	s_add_i32 s65, 0, 0x10000
	v_add_u32_e32 v140, s65, v143
	ds_read_b128 v[146:149], v140
	ds_read_b128 v[150:153], v140 offset:1024
	ds_read_b128 v[154:157], v140 offset:2048
	ds_read_b128 v[158:161], v140 offset:3072
	s_cmp_eq_u32 s64, 12
	s_cselect_b32 s37, s25, s35
	s_cselect_b32 s36, s56, s34
	s_cselect_b32 s35, s23, s63
	s_cselect_b32 s34, s57, s59
	v_lshl_add_u64 v[140:141], s[30:31], 0, v[136:137]
	s_add_i32 m0, s21, 0xc000
	ds_read_b128 v[162:165], v145
	ds_read_b128 v[166:169], v145 offset:1024
	ds_read_b128 v[170:173], v145 offset:2048
	ds_read_b128 v[176:179], v145 offset:3072
	ds_read_b128 v[180:183], v145 offset:4096
	ds_read_b128 v[184:187], v145 offset:5120
	ds_read_b128 v[188:191], v145 offset:6144
	ds_read_b128 v[192:195], v145 offset:7168
	global_load_lds_dwordx4 v[140:141], off
	v_lshl_add_u64 v[140:141], s[30:31], 0, v[138:139]
	s_add_i32 m0, s21, 0xe000
	s_nop 0
	global_load_lds_dwordx4 v[140:141], off
	s_waitcnt lgkmcnt(8)
	s_barrier
	s_setprio 1
	s_waitcnt lgkmcnt(7)
	v_mfma_f32_16x16x32_bf16 v[126:129], v[146:149], v[162:165], v[126:129]
	v_mfma_f32_16x16x32_bf16 v[122:125], v[154:157], v[162:165], v[122:125]
	s_waitcnt lgkmcnt(5)
	v_mfma_f32_16x16x32_bf16 v[118:121], v[146:149], v[170:173], v[118:121]
	v_mfma_f32_16x16x32_bf16 v[110:113], v[154:157], v[170:173], v[110:113]
	s_waitcnt lgkmcnt(3)
	v_mfma_f32_16x16x32_bf16 v[102:105], v[146:149], v[180:183], v[102:105]
	v_mfma_f32_16x16x32_bf16 v[94:97], v[154:157], v[180:183], v[94:97]
	s_waitcnt lgkmcnt(1)
	v_mfma_f32_16x16x32_bf16 v[86:89], v[146:149], v[188:191], v[86:89]
	v_mfma_f32_16x16x32_bf16 v[78:81], v[154:157], v[188:191], v[78:81]
	v_mfma_f32_16x16x32_bf16 v[126:129], v[150:153], v[166:169], v[126:129]
	v_mfma_f32_16x16x32_bf16 v[122:125], v[158:161], v[166:169], v[122:125]
	v_mfma_f32_16x16x32_bf16 v[118:121], v[150:153], v[176:179], v[118:121]
	v_mfma_f32_16x16x32_bf16 v[110:113], v[158:161], v[176:179], v[110:113]
	v_mfma_f32_16x16x32_bf16 v[102:105], v[150:153], v[184:187], v[102:105]
	v_mfma_f32_16x16x32_bf16 v[94:97], v[158:161], v[184:187], v[94:97]
	s_waitcnt lgkmcnt(0)
	v_mfma_f32_16x16x32_bf16 v[86:89], v[150:153], v[192:195], v[86:89]
	v_mfma_f32_16x16x32_bf16 v[78:81], v[158:161], v[192:195], v[78:81]
	s_setprio 0
	s_barrier
	s_add_i32 s68, 0, 0x14000
	v_add_u32_e32 v140, s68, v143
	s_add_i32 s65, s65, s13
	ds_read_b128 v[196:199], v140
	ds_read_b128 v[200:203], v140 offset:1024
	ds_read_b128 v[204:207], v140 offset:2048
	ds_read_b128 v[208:211], v140 offset:3072
	v_lshl_add_u64 v[140:141], s[34:35], 0, v[48:49]
	s_mov_b32 m0, s65
	v_lshl_add_u64 v[212:213], s[34:35], 0, v[130:131]
	global_load_lds_dwordx4 v[140:141], off
	s_add_i32 m0, s65, 0x2000
	s_nop 0
	global_load_lds_dwordx4 v[212:213], off
	s_barrier
	s_setprio 1
	s_waitcnt lgkmcnt(3)
	v_mfma_f32_16x16x32_bf16 v[114:117], v[196:199], v[162:165], v[114:117]
	s_waitcnt lgkmcnt(1)
	v_mfma_f32_16x16x32_bf16 v[106:109], v[204:207], v[162:165], v[106:109]
	v_mfma_f32_16x16x32_bf16 v[98:101], v[196:199], v[170:173], v[98:101]
	v_mfma_f32_16x16x32_bf16 v[90:93], v[204:207], v[170:173], v[90:93]
	v_mfma_f32_16x16x32_bf16 v[82:85], v[196:199], v[180:183], v[82:85]
	v_mfma_f32_16x16x32_bf16 v[74:77], v[204:207], v[180:183], v[74:77]
	v_mfma_f32_16x16x32_bf16 v[70:73], v[196:199], v[188:191], v[70:73]
	v_mfma_f32_16x16x32_bf16 v[66:69], v[204:207], v[188:191], v[66:69]
	v_mfma_f32_16x16x32_bf16 v[114:117], v[200:203], v[166:169], v[114:117]
	s_waitcnt lgkmcnt(0)
	v_mfma_f32_16x16x32_bf16 v[106:109], v[208:211], v[166:169], v[106:109]
	v_mfma_f32_16x16x32_bf16 v[98:101], v[200:203], v[176:179], v[98:101]
	v_mfma_f32_16x16x32_bf16 v[90:93], v[208:211], v[176:179], v[90:93]
	v_mfma_f32_16x16x32_bf16 v[82:85], v[200:203], v[184:187], v[82:85]
	v_mfma_f32_16x16x32_bf16 v[74:77], v[208:211], v[184:187], v[74:77]
	v_mfma_f32_16x16x32_bf16 v[70:73], v[200:203], v[192:195], v[70:73]
	v_mfma_f32_16x16x32_bf16 v[66:69], v[208:211], v[192:195], v[66:69]
	s_setprio 0
	s_mov_b32 m0, s21
	v_lshl_add_u64 v[214:215], s[36:37], 0, v[134:135]
	s_barrier
	ds_read_b128 v[162:165], v145 offset:16384
	ds_read_b128 v[166:169], v145 offset:17408
	ds_read_b128 v[170:173], v145 offset:18432
	ds_read_b128 v[176:179], v145 offset:19456
	ds_read_b128 v[180:183], v145 offset:20480
	ds_read_b128 v[184:187], v145 offset:21504
	ds_read_b128 v[188:191], v145 offset:22528
	ds_read_b128 v[192:195], v145 offset:23552
	global_load_lds_dwordx4 v[214:215], off
	v_lshl_add_u64 v[216:217], s[36:37], 0, v[132:133]
	s_mov_b32 m0, s46
	s_nop 0
	global_load_lds_dwordx4 v[216:217], off
	s_barrier
	s_setprio 1
	s_waitcnt lgkmcnt(7)
	v_mfma_f32_16x16x32_bf16 v[62:65], v[146:149], v[162:165], v[62:65]
	v_mfma_f32_16x16x32_bf16 v[58:61], v[154:157], v[162:165], v[58:61]
	s_waitcnt lgkmcnt(5)
	v_mfma_f32_16x16x32_bf16 v[54:57], v[146:149], v[170:173], v[54:57]
	v_mfma_f32_16x16x32_bf16 v[44:47], v[154:157], v[170:173], v[44:47]
	s_waitcnt lgkmcnt(3)
	v_mfma_f32_16x16x32_bf16 v[36:39], v[146:149], v[180:183], v[36:39]
	v_mfma_f32_16x16x32_bf16 v[28:31], v[154:157], v[180:183], v[28:31]
	s_waitcnt lgkmcnt(1)
	v_mfma_f32_16x16x32_bf16 v[20:23], v[146:149], v[188:191], v[20:23]
	v_mfma_f32_16x16x32_bf16 v[12:15], v[154:157], v[188:191], v[12:15]
	v_mfma_f32_16x16x32_bf16 v[62:65], v[150:153], v[166:169], v[62:65]
	v_mfma_f32_16x16x32_bf16 v[58:61], v[158:161], v[166:169], v[58:61]
	v_mfma_f32_16x16x32_bf16 v[54:57], v[150:153], v[176:179], v[54:57]
	v_mfma_f32_16x16x32_bf16 v[44:47], v[158:161], v[176:179], v[44:47]
	v_mfma_f32_16x16x32_bf16 v[36:39], v[150:153], v[184:187], v[36:39]
	v_mfma_f32_16x16x32_bf16 v[28:31], v[158:161], v[184:187], v[28:31]
	s_waitcnt lgkmcnt(0)
	v_mfma_f32_16x16x32_bf16 v[20:23], v[150:153], v[192:195], v[20:23]
	v_mfma_f32_16x16x32_bf16 v[12:15], v[158:161], v[192:195], v[12:15]
	s_setprio 0
	s_barrier
	s_add_u32 s66, s34, 0x40000
	s_addc_u32 s67, s35, 0
	s_add_i32 s65, s68, s13
	v_lshl_add_u64 v[146:147], s[66:67], 0, v[48:49]
	s_mov_b32 m0, s65
	s_nop 0
	global_load_lds_dwordx4 v[146:147], off
	v_lshl_add_u64 v[146:147], s[66:67], 0, v[130:131]
	s_add_i32 m0, s65, 0x2000
	s_nop 0
	global_load_lds_dwordx4 v[146:147], off
	s_waitcnt vmcnt(6)
	s_barrier
	s_setprio 1
	v_mfma_f32_16x16x32_bf16 v[50:53], v[196:199], v[162:165], v[50:53]
	v_mfma_f32_16x16x32_bf16 v[40:43], v[204:207], v[162:165], v[40:43]
	v_mfma_f32_16x16x32_bf16 v[32:35], v[196:199], v[170:173], v[32:35]
	v_mfma_f32_16x16x32_bf16 v[24:27], v[204:207], v[170:173], v[24:27]
	v_mfma_f32_16x16x32_bf16 v[16:19], v[196:199], v[180:183], v[16:19]
	v_mfma_f32_16x16x32_bf16 v[8:11], v[204:207], v[180:183], v[8:11]
	v_mfma_f32_16x16x32_bf16 v[4:7], v[196:199], v[188:191], v[4:7]
	v_mfma_f32_16x16x32_bf16 v[0:3], v[204:207], v[188:191], v[0:3]
	v_mfma_f32_16x16x32_bf16 v[50:53], v[200:203], v[166:169], v[50:53]
	v_mfma_f32_16x16x32_bf16 v[40:43], v[208:211], v[166:169], v[40:43]
	v_mfma_f32_16x16x32_bf16 v[32:35], v[200:203], v[176:179], v[32:35]
	v_mfma_f32_16x16x32_bf16 v[24:27], v[208:211], v[176:179], v[24:27]
	v_mfma_f32_16x16x32_bf16 v[16:19], v[200:203], v[184:187], v[16:19]
	v_mfma_f32_16x16x32_bf16 v[8:11], v[208:211], v[184:187], v[8:11]
	v_mfma_f32_16x16x32_bf16 v[4:7], v[200:203], v[192:195], v[4:7]
	v_mfma_f32_16x16x32_bf16 v[0:3], v[208:211], v[192:195], v[0:3]
	s_setprio 0
	s_add_i32 s65, 0, 0x18000
	v_add_u32_e32 v158, s65, v143
	s_barrier
	ds_read_b128 v[146:149], v158
	ds_read_b128 v[150:153], v158 offset:1024
	ds_read_b128 v[154:157], v158 offset:2048
	ds_read_b128 v[158:161], v158 offset:3072
	s_add_u32 s36, s36, 0x40000
	s_addc_u32 s37, s37, 0
	s_mov_b32 m0, s47
	v_lshl_add_u64 v[196:197], s[36:37], 0, v[134:135]
	ds_read_b128 v[162:165], v145 offset:32768
	ds_read_b128 v[166:169], v145 offset:33792
	ds_read_b128 v[170:173], v145 offset:34816
	ds_read_b128 v[176:179], v145 offset:35840
	ds_read_b128 v[180:183], v145 offset:36864
	ds_read_b128 v[184:187], v145 offset:37888
	ds_read_b128 v[188:191], v145 offset:38912
	ds_read_b128 v[192:195], v145 offset:39936
	global_load_lds_dwordx4 v[196:197], off
	v_lshl_add_u64 v[196:197], s[36:37], 0, v[132:133]
	s_mov_b32 m0, s48
	s_nop 0
	global_load_lds_dwordx4 v[196:197], off
	s_waitcnt lgkmcnt(8)
	s_barrier
	s_setprio 1
	s_waitcnt lgkmcnt(7)
	v_mfma_f32_16x16x32_bf16 v[126:129], v[146:149], v[162:165], v[126:129]
	v_mfma_f32_16x16x32_bf16 v[122:125], v[154:157], v[162:165], v[122:125]
	s_waitcnt lgkmcnt(5)
	v_mfma_f32_16x16x32_bf16 v[118:121], v[146:149], v[170:173], v[118:121]
	v_mfma_f32_16x16x32_bf16 v[110:113], v[154:157], v[170:173], v[110:113]
	s_waitcnt lgkmcnt(3)
	v_mfma_f32_16x16x32_bf16 v[102:105], v[146:149], v[180:183], v[102:105]
	v_mfma_f32_16x16x32_bf16 v[94:97], v[154:157], v[180:183], v[94:97]
	s_waitcnt lgkmcnt(1)
	v_mfma_f32_16x16x32_bf16 v[86:89], v[146:149], v[188:191], v[86:89]
	v_mfma_f32_16x16x32_bf16 v[78:81], v[154:157], v[188:191], v[78:81]
	v_mfma_f32_16x16x32_bf16 v[126:129], v[150:153], v[166:169], v[126:129]
	v_mfma_f32_16x16x32_bf16 v[122:125], v[158:161], v[166:169], v[122:125]
	v_mfma_f32_16x16x32_bf16 v[118:121], v[150:153], v[176:179], v[118:121]
	v_mfma_f32_16x16x32_bf16 v[110:113], v[158:161], v[176:179], v[110:113]
	v_mfma_f32_16x16x32_bf16 v[102:105], v[150:153], v[184:187], v[102:105]
	v_mfma_f32_16x16x32_bf16 v[94:97], v[158:161], v[184:187], v[94:97]
	s_waitcnt lgkmcnt(0)
	v_mfma_f32_16x16x32_bf16 v[86:89], v[150:153], v[192:195], v[86:89]
	v_mfma_f32_16x16x32_bf16 v[78:81], v[158:161], v[192:195], v[78:81]
	s_setprio 0
	s_barrier
	s_add_i32 s36, 0, 0x1c000
	s_add_i32 s37, s65, s13
	v_add_u32_e32 v175, s36, v143
	v_lshl_add_u64 v[140:141], v[140:141], 0, s[0:1]
	s_mov_b32 m0, s37
	ds_read_b128 v[196:199], v175
	ds_read_b128 v[200:203], v175 offset:1024
	ds_read_b128 v[204:207], v175 offset:2048
	ds_read_b128 v[208:211], v175 offset:3072
	global_load_lds_dwordx4 v[140:141], off
	v_lshl_add_u64 v[140:141], v[212:213], 0, s[0:1]
	s_add_i32 m0, s37, 0x2000
	s_nop 0
	global_load_lds_dwordx4 v[140:141], off
	s_barrier
	s_setprio 1
	s_waitcnt lgkmcnt(3)
	v_mfma_f32_16x16x32_bf16 v[114:117], v[196:199], v[162:165], v[114:117]
	s_waitcnt lgkmcnt(1)
	v_mfma_f32_16x16x32_bf16 v[106:109], v[204:207], v[162:165], v[106:109]
	v_mfma_f32_16x16x32_bf16 v[98:101], v[196:199], v[170:173], v[98:101]
	v_mfma_f32_16x16x32_bf16 v[90:93], v[204:207], v[170:173], v[90:93]
	v_mfma_f32_16x16x32_bf16 v[82:85], v[196:199], v[180:183], v[82:85]
	v_mfma_f32_16x16x32_bf16 v[74:77], v[204:207], v[180:183], v[74:77]
	v_mfma_f32_16x16x32_bf16 v[70:73], v[196:199], v[188:191], v[70:73]
	v_mfma_f32_16x16x32_bf16 v[66:69], v[204:207], v[188:191], v[66:69]
	v_mfma_f32_16x16x32_bf16 v[114:117], v[200:203], v[166:169], v[114:117]
	s_waitcnt lgkmcnt(0)
	v_mfma_f32_16x16x32_bf16 v[106:109], v[208:211], v[166:169], v[106:109]
	v_mfma_f32_16x16x32_bf16 v[98:101], v[200:203], v[176:179], v[98:101]
	v_mfma_f32_16x16x32_bf16 v[90:93], v[208:211], v[176:179], v[90:93]
	v_mfma_f32_16x16x32_bf16 v[82:85], v[200:203], v[184:187], v[82:85]
	v_mfma_f32_16x16x32_bf16 v[74:77], v[208:211], v[184:187], v[74:77]
	v_mfma_f32_16x16x32_bf16 v[70:73], v[200:203], v[192:195], v[70:73]
	v_mfma_f32_16x16x32_bf16 v[66:69], v[208:211], v[192:195], v[66:69]
	s_setprio 0
	s_mov_b32 m0, s49
	v_lshl_add_u64 v[140:141], v[214:215], 0, s[0:1]
	s_barrier
	ds_read_b128 v[162:165], v145 offset:49152
	ds_read_b128 v[166:169], v145 offset:50176
	ds_read_b128 v[170:173], v145 offset:51200
	ds_read_b128 v[176:179], v145 offset:52224
	ds_read_b128 v[180:183], v145 offset:53248
	ds_read_b128 v[184:187], v145 offset:54272
	ds_read_b128 v[188:191], v145 offset:55296
	ds_read_b128 v[192:195], v145 offset:56320
	global_load_lds_dwordx4 v[140:141], off
	v_lshl_add_u64 v[140:141], v[216:217], 0, s[0:1]
	s_mov_b32 m0, s50
	s_nop 0
	global_load_lds_dwordx4 v[140:141], off
	s_barrier
	s_setprio 1
	s_waitcnt lgkmcnt(7)
	v_mfma_f32_16x16x32_bf16 v[62:65], v[146:149], v[162:165], v[62:65]
	v_mfma_f32_16x16x32_bf16 v[58:61], v[154:157], v[162:165], v[58:61]
	s_waitcnt lgkmcnt(5)
	v_mfma_f32_16x16x32_bf16 v[54:57], v[146:149], v[170:173], v[54:57]
	v_mfma_f32_16x16x32_bf16 v[44:47], v[154:157], v[170:173], v[44:47]
	s_waitcnt lgkmcnt(3)
	v_mfma_f32_16x16x32_bf16 v[36:39], v[146:149], v[180:183], v[36:39]
	v_mfma_f32_16x16x32_bf16 v[28:31], v[154:157], v[180:183], v[28:31]
	s_waitcnt lgkmcnt(1)
	v_mfma_f32_16x16x32_bf16 v[20:23], v[146:149], v[188:191], v[20:23]
	v_mfma_f32_16x16x32_bf16 v[12:15], v[154:157], v[188:191], v[12:15]
	v_mfma_f32_16x16x32_bf16 v[62:65], v[150:153], v[166:169], v[62:65]
	v_mfma_f32_16x16x32_bf16 v[58:61], v[158:161], v[166:169], v[58:61]
	v_mfma_f32_16x16x32_bf16 v[54:57], v[150:153], v[176:179], v[54:57]
	v_mfma_f32_16x16x32_bf16 v[44:47], v[158:161], v[176:179], v[44:47]
	v_mfma_f32_16x16x32_bf16 v[36:39], v[150:153], v[184:187], v[36:39]
	v_mfma_f32_16x16x32_bf16 v[28:31], v[158:161], v[184:187], v[28:31]
	s_waitcnt lgkmcnt(0)
	v_mfma_f32_16x16x32_bf16 v[20:23], v[150:153], v[192:195], v[20:23]
	v_mfma_f32_16x16x32_bf16 v[12:15], v[158:161], v[192:195], v[12:15]
	s_setprio 0
	s_barrier
	s_add_u32 s34, s34, 0x40080
	s_addc_u32 s35, s35, 0
	s_add_i32 s36, s36, s13
	v_lshl_add_u64 v[140:141], s[34:35], 0, v[48:49]
	s_mov_b32 m0, s36
	s_nop 0
	global_load_lds_dwordx4 v[140:141], off
	v_lshl_add_u64 v[140:141], s[34:35], 0, v[130:131]
	s_add_i32 m0, s36, 0x2000
	s_nop 0
	global_load_lds_dwordx4 v[140:141], off
	s_waitcnt vmcnt(6)
	s_barrier
	s_setprio 1
	v_mfma_f32_16x16x32_bf16 v[50:53], v[196:199], v[162:165], v[50:53]
	v_mfma_f32_16x16x32_bf16 v[40:43], v[204:207], v[162:165], v[40:43]
	v_mfma_f32_16x16x32_bf16 v[32:35], v[196:199], v[170:173], v[32:35]
	v_mfma_f32_16x16x32_bf16 v[24:27], v[204:207], v[170:173], v[24:27]
	v_mfma_f32_16x16x32_bf16 v[16:19], v[196:199], v[180:183], v[16:19]
	v_mfma_f32_16x16x32_bf16 v[8:11], v[204:207], v[180:183], v[8:11]
	v_mfma_f32_16x16x32_bf16 v[4:7], v[196:199], v[188:191], v[4:7]
	v_mfma_f32_16x16x32_bf16 v[0:3], v[204:207], v[188:191], v[0:3]
	v_mfma_f32_16x16x32_bf16 v[50:53], v[200:203], v[166:169], v[50:53]
	v_mfma_f32_16x16x32_bf16 v[40:43], v[208:211], v[166:169], v[40:43]
	v_mfma_f32_16x16x32_bf16 v[32:35], v[200:203], v[176:179], v[32:35]
	v_mfma_f32_16x16x32_bf16 v[24:27], v[208:211], v[176:179], v[24:27]
	v_mfma_f32_16x16x32_bf16 v[16:19], v[200:203], v[184:187], v[16:19]
	v_mfma_f32_16x16x32_bf16 v[8:11], v[208:211], v[184:187], v[8:11]
	v_mfma_f32_16x16x32_bf16 v[4:7], v[200:203], v[192:195], v[4:7]
	v_mfma_f32_16x16x32_bf16 v[0:3], v[208:211], v[192:195], v[0:3]
	s_setprio 0
	s_add_i32 s64, s64, 2
	s_add_u32 s30, s30, 0x100
	s_addc_u32 s31, s31, 0
	s_add_u32 s59, s59, 0x100
	s_addc_u32 s63, s63, 0
	s_cmp_gt_u32 s64, 13
	s_barrier
	s_cbranch_scc0 .LBB0_320
	s_andn2_b64 vcc, exec, s[16:17]
	s_lshl_b32 s23, s55, 8
	s_cbranch_vccz .LBB0_315
	s_mov_b64 s[30:31], s[2:3]
	s_branch .LBB0_316

.LBB0_335:
	s_add_u32 s12, s6, 0xfffc0080
	s_addc_u32 s13, s7, -1
	s_add_i32 s57, 0, 0x10000
	v_add_u32_e32 v48, s57, v166
	ds_read_b128 v[144:147], v48
	ds_read_b128 v[148:151], v48 offset:1024
	ds_read_b128 v[152:155], v48 offset:2048
	ds_read_b128 v[156:159], v48 offset:3072
	s_cmp_eq_u32 s56, 12
	s_cselect_b32 s17, s23, s13
	s_cselect_b32 s16, s50, s12
	s_cselect_b32 s13, s21, s55
	s_cselect_b32 s12, s51, s54
	v_lshl_add_u64 v[164:165], s[6:7], 0, v[140:141]
	s_add_i32 m0, s3, 0xc000
	ds_read_b128 v[160:163], v167
	ds_read_b128 v[168:171], v167 offset:1024
	ds_read_b128 v[176:179], v167 offset:2048
	ds_read_b128 v[180:183], v167 offset:3072
	ds_read_b128 v[184:187], v167 offset:4096
	ds_read_b128 v[188:191], v167 offset:5120
	ds_read_b128 v[192:195], v167 offset:6144
	ds_read_b128 v[196:199], v167 offset:7168
	global_load_lds_dwordx4 v[164:165], off
	v_lshl_add_u64 v[164:165], s[6:7], 0, v[142:143]
	s_add_i32 m0, s3, 0xe000
	s_nop 0
	global_load_lds_dwordx4 v[164:165], off
	s_waitcnt lgkmcnt(8)
	s_barrier
	s_setprio 1
	s_waitcnt lgkmcnt(7)
	v_mfma_f32_16x16x32_bf16 v[126:129], v[144:147], v[160:163], v[126:129]
	v_mfma_f32_16x16x32_bf16 v[122:125], v[152:155], v[160:163], v[122:125]
	s_waitcnt lgkmcnt(5)
	v_mfma_f32_16x16x32_bf16 v[110:113], v[144:147], v[176:179], v[110:113]
	v_mfma_f32_16x16x32_bf16 v[106:109], v[152:155], v[176:179], v[106:109]
	s_waitcnt lgkmcnt(3)
	v_mfma_f32_16x16x32_bf16 v[94:97], v[144:147], v[184:187], v[94:97]
	v_mfma_f32_16x16x32_bf16 v[90:93], v[152:155], v[184:187], v[90:93]
	s_waitcnt lgkmcnt(1)
	v_mfma_f32_16x16x32_bf16 v[78:81], v[144:147], v[192:195], v[78:81]
	v_mfma_f32_16x16x32_bf16 v[74:77], v[152:155], v[192:195], v[74:77]
	v_mfma_f32_16x16x32_bf16 v[126:129], v[148:151], v[168:171], v[126:129]
	v_mfma_f32_16x16x32_bf16 v[122:125], v[156:159], v[168:171], v[122:125]
	v_mfma_f32_16x16x32_bf16 v[110:113], v[148:151], v[180:183], v[110:113]
	v_mfma_f32_16x16x32_bf16 v[106:109], v[156:159], v[180:183], v[106:109]
	v_mfma_f32_16x16x32_bf16 v[94:97], v[148:151], v[188:191], v[94:97]
	v_mfma_f32_16x16x32_bf16 v[90:93], v[156:159], v[188:191], v[90:93]
	s_waitcnt lgkmcnt(0)
	v_mfma_f32_16x16x32_bf16 v[78:81], v[148:151], v[196:199], v[78:81]
	v_mfma_f32_16x16x32_bf16 v[74:77], v[156:159], v[196:199], v[74:77]
	s_setprio 0
	s_barrier
	s_add_i32 s59, 0, 0x14000
	s_add_i32 s57, s57, s34
	v_add_u32_e32 v48, s59, v166
	v_lshl_add_u64 v[164:165], s[12:13], 0, v[134:135]
	s_mov_b32 m0, s57
	ds_read_b128 v[200:203], v48
	ds_read_b128 v[204:207], v48 offset:1024
	ds_read_b128 v[208:211], v48 offset:2048
	ds_read_b128 v[212:215], v48 offset:3072
	global_load_lds_dwordx4 v[164:165], off
	v_lshl_add_u64 v[172:173], s[12:13], 0, v[130:131]
	s_add_i32 m0, s57, 0x2000
	s_nop 0
	global_load_lds_dwordx4 v[172:173], off
	s_barrier
	s_setprio 1
	s_waitcnt lgkmcnt(3)
	v_mfma_f32_16x16x32_bf16 v[118:121], v[200:203], v[160:163], v[118:121]
	s_waitcnt lgkmcnt(1)
	v_mfma_f32_16x16x32_bf16 v[114:117], v[208:211], v[160:163], v[114:117]
	v_mfma_f32_16x16x32_bf16 v[102:105], v[200:203], v[176:179], v[102:105]
	v_mfma_f32_16x16x32_bf16 v[98:101], v[208:211], v[176:179], v[98:101]
	v_mfma_f32_16x16x32_bf16 v[86:89], v[200:203], v[184:187], v[86:89]
	v_mfma_f32_16x16x32_bf16 v[82:85], v[208:211], v[184:187], v[82:85]
	v_mfma_f32_16x16x32_bf16 v[70:73], v[200:203], v[192:195], v[70:73]
	v_mfma_f32_16x16x32_bf16 v[66:69], v[208:211], v[192:195], v[66:69]
	v_mfma_f32_16x16x32_bf16 v[118:121], v[204:207], v[168:171], v[118:121]
	s_waitcnt lgkmcnt(0)
	v_mfma_f32_16x16x32_bf16 v[114:117], v[212:215], v[168:171], v[114:117]
	v_mfma_f32_16x16x32_bf16 v[102:105], v[204:207], v[180:183], v[102:105]
	v_mfma_f32_16x16x32_bf16 v[98:101], v[212:215], v[180:183], v[98:101]
	v_mfma_f32_16x16x32_bf16 v[86:89], v[204:207], v[188:191], v[86:89]
	v_mfma_f32_16x16x32_bf16 v[82:85], v[212:215], v[188:191], v[82:85]
	v_mfma_f32_16x16x32_bf16 v[70:73], v[204:207], v[196:199], v[70:73]
	v_mfma_f32_16x16x32_bf16 v[66:69], v[212:215], v[196:199], v[66:69]
	s_setprio 0
	s_mov_b32 m0, s3
	v_lshl_add_u64 v[216:217], s[16:17], 0, v[136:137]
	s_barrier
	ds_read_b128 v[160:163], v167 offset:16384
	ds_read_b128 v[168:171], v167 offset:17408
	ds_read_b128 v[176:179], v167 offset:18432
	ds_read_b128 v[180:183], v167 offset:19456
	ds_read_b128 v[184:187], v167 offset:20480
	ds_read_b128 v[188:191], v167 offset:21504
	ds_read_b128 v[192:195], v167 offset:22528
	ds_read_b128 v[196:199], v167 offset:23552
	global_load_lds_dwordx4 v[216:217], off
	v_lshl_add_u64 v[218:219], s[16:17], 0, v[132:133]
	s_mov_b32 m0, s36
	s_nop 0
	global_load_lds_dwordx4 v[218:219], off
	s_barrier
	s_setprio 1
	s_waitcnt lgkmcnt(7)
	v_mfma_f32_16x16x32_bf16 v[62:65], v[144:147], v[160:163], v[62:65]
	v_mfma_f32_16x16x32_bf16 v[58:61], v[152:155], v[160:163], v[58:61]
	s_waitcnt lgkmcnt(5)
	v_mfma_f32_16x16x32_bf16 v[44:47], v[144:147], v[176:179], v[44:47]
	v_mfma_f32_16x16x32_bf16 v[40:43], v[152:155], v[176:179], v[40:43]
	s_waitcnt lgkmcnt(3)
	v_mfma_f32_16x16x32_bf16 v[28:31], v[144:147], v[184:187], v[28:31]
	v_mfma_f32_16x16x32_bf16 v[24:27], v[152:155], v[184:187], v[24:27]
	s_waitcnt lgkmcnt(1)
	v_mfma_f32_16x16x32_bf16 v[12:15], v[144:147], v[192:195], v[12:15]
	v_mfma_f32_16x16x32_bf16 v[8:11], v[152:155], v[192:195], v[8:11]
	v_mfma_f32_16x16x32_bf16 v[62:65], v[148:151], v[168:171], v[62:65]
	v_mfma_f32_16x16x32_bf16 v[58:61], v[156:159], v[168:171], v[58:61]
	v_mfma_f32_16x16x32_bf16 v[44:47], v[148:151], v[180:183], v[44:47]
	v_mfma_f32_16x16x32_bf16 v[40:43], v[156:159], v[180:183], v[40:43]
	v_mfma_f32_16x16x32_bf16 v[28:31], v[148:151], v[188:191], v[28:31]
	v_mfma_f32_16x16x32_bf16 v[24:27], v[156:159], v[188:191], v[24:27]
	s_waitcnt lgkmcnt(0)
	v_mfma_f32_16x16x32_bf16 v[12:15], v[148:151], v[196:199], v[12:15]
	v_mfma_f32_16x16x32_bf16 v[8:11], v[156:159], v[196:199], v[8:11]
	s_setprio 0
	s_barrier
	s_add_u32 s64, s12, 0x40000
	s_addc_u32 s65, s13, 0
	s_add_i32 s57, s59, s34
	v_lshl_add_u64 v[144:145], s[64:65], 0, v[134:135]
	s_mov_b32 m0, s57
	s_nop 0
	global_load_lds_dwordx4 v[144:145], off
	v_lshl_add_u64 v[144:145], s[64:65], 0, v[130:131]
	s_add_i32 m0, s57, 0x2000
	s_nop 0
	global_load_lds_dwordx4 v[144:145], off
	s_waitcnt vmcnt(6)
	s_barrier
	s_setprio 1
	v_mfma_f32_16x16x32_bf16 v[54:57], v[200:203], v[160:163], v[54:57]
	v_mfma_f32_16x16x32_bf16 v[50:53], v[208:211], v[160:163], v[50:53]
	v_mfma_f32_16x16x32_bf16 v[36:39], v[200:203], v[176:179], v[36:39]
	v_mfma_f32_16x16x32_bf16 v[32:35], v[208:211], v[176:179], v[32:35]
	v_mfma_f32_16x16x32_bf16 v[20:23], v[200:203], v[184:187], v[20:23]
	v_mfma_f32_16x16x32_bf16 v[16:19], v[208:211], v[184:187], v[16:19]
	v_mfma_f32_16x16x32_bf16 v[4:7], v[200:203], v[192:195], v[4:7]
	v_mfma_f32_16x16x32_bf16 v[0:3], v[208:211], v[192:195], v[0:3]
	v_mfma_f32_16x16x32_bf16 v[54:57], v[204:207], v[168:171], v[54:57]
	v_mfma_f32_16x16x32_bf16 v[50:53], v[212:215], v[168:171], v[50:53]
	v_mfma_f32_16x16x32_bf16 v[36:39], v[204:207], v[180:183], v[36:39]
	v_mfma_f32_16x16x32_bf16 v[32:35], v[212:215], v[180:183], v[32:35]
	v_mfma_f32_16x16x32_bf16 v[20:23], v[204:207], v[188:191], v[20:23]
	v_mfma_f32_16x16x32_bf16 v[16:19], v[212:215], v[188:191], v[16:19]
	v_mfma_f32_16x16x32_bf16 v[4:7], v[204:207], v[196:199], v[4:7]
	v_mfma_f32_16x16x32_bf16 v[0:3], v[212:215], v[196:199], v[0:3]
	s_setprio 0
	s_add_i32 s57, 0, 0x18000
	v_add_u32_e32 v48, s57, v166
	s_barrier
	ds_read_b128 v[144:147], v48
	ds_read_b128 v[148:151], v48 offset:1024
	ds_read_b128 v[152:155], v48 offset:2048
	ds_read_b128 v[156:159], v48 offset:3072
	s_add_u32 s16, s16, 0x40000
	s_addc_u32 s17, s17, 0
	s_mov_b32 m0, s37
	v_lshl_add_u64 v[200:201], s[16:17], 0, v[136:137]
	ds_read_b128 v[160:163], v167 offset:32768
	ds_read_b128 v[168:171], v167 offset:33792
	ds_read_b128 v[176:179], v167 offset:34816
	ds_read_b128 v[180:183], v167 offset:35840
	ds_read_b128 v[184:187], v167 offset:36864
	ds_read_b128 v[188:191], v167 offset:37888
	ds_read_b128 v[192:195], v167 offset:38912
	ds_read_b128 v[196:199], v167 offset:39936
	global_load_lds_dwordx4 v[200:201], off
	v_lshl_add_u64 v[200:201], s[16:17], 0, v[132:133]
	s_mov_b32 m0, s38
	s_nop 0
	global_load_lds_dwordx4 v[200:201], off
	s_waitcnt lgkmcnt(8)
	s_barrier
	s_setprio 1
	s_waitcnt lgkmcnt(7)
	v_mfma_f32_16x16x32_bf16 v[126:129], v[144:147], v[160:163], v[126:129]
	v_mfma_f32_16x16x32_bf16 v[122:125], v[152:155], v[160:163], v[122:125]
	s_waitcnt lgkmcnt(5)
	v_mfma_f32_16x16x32_bf16 v[110:113], v[144:147], v[176:179], v[110:113]
	v_mfma_f32_16x16x32_bf16 v[106:109], v[152:155], v[176:179], v[106:109]
	s_waitcnt lgkmcnt(3)
	v_mfma_f32_16x16x32_bf16 v[94:97], v[144:147], v[184:187], v[94:97]
	v_mfma_f32_16x16x32_bf16 v[90:93], v[152:155], v[184:187], v[90:93]
	s_waitcnt lgkmcnt(1)
	v_mfma_f32_16x16x32_bf16 v[78:81], v[144:147], v[192:195], v[78:81]
	v_mfma_f32_16x16x32_bf16 v[74:77], v[152:155], v[192:195], v[74:77]
	v_mfma_f32_16x16x32_bf16 v[126:129], v[148:151], v[168:171], v[126:129]
	v_mfma_f32_16x16x32_bf16 v[122:125], v[156:159], v[168:171], v[122:125]
	v_mfma_f32_16x16x32_bf16 v[110:113], v[148:151], v[180:183], v[110:113]
	v_mfma_f32_16x16x32_bf16 v[106:109], v[156:159], v[180:183], v[106:109]
	v_mfma_f32_16x16x32_bf16 v[94:97], v[148:151], v[188:191], v[94:97]
	v_mfma_f32_16x16x32_bf16 v[90:93], v[156:159], v[188:191], v[90:93]
	s_waitcnt lgkmcnt(0)
	v_mfma_f32_16x16x32_bf16 v[78:81], v[148:151], v[196:199], v[78:81]
	v_mfma_f32_16x16x32_bf16 v[74:77], v[156:159], v[196:199], v[74:77]
	s_setprio 0
	s_barrier
	s_add_i32 s16, 0, 0x1c000
	s_add_i32 s17, s57, s34
	v_add_u32_e32 v48, s16, v166
	v_lshl_add_u64 v[164:165], v[164:165], 0, s[0:1]
	s_mov_b32 m0, s17
	ds_read_b128 v[200:203], v48
	ds_read_b128 v[204:207], v48 offset:1024
	ds_read_b128 v[208:211], v48 offset:2048
	ds_read_b128 v[212:215], v48 offset:3072
	global_load_lds_dwordx4 v[164:165], off
	v_lshl_add_u64 v[164:165], v[172:173], 0, s[0:1]
	s_add_i32 m0, s17, 0x2000
	s_nop 0
	global_load_lds_dwordx4 v[164:165], off
	s_barrier
	s_setprio 1
	s_waitcnt lgkmcnt(3)
	v_mfma_f32_16x16x32_bf16 v[118:121], v[200:203], v[160:163], v[118:121]
	s_waitcnt lgkmcnt(1)
	v_mfma_f32_16x16x32_bf16 v[114:117], v[208:211], v[160:163], v[114:117]
	v_mfma_f32_16x16x32_bf16 v[102:105], v[200:203], v[176:179], v[102:105]
	v_mfma_f32_16x16x32_bf16 v[98:101], v[208:211], v[176:179], v[98:101]
	v_mfma_f32_16x16x32_bf16 v[86:89], v[200:203], v[184:187], v[86:89]
	v_mfma_f32_16x16x32_bf16 v[82:85], v[208:211], v[184:187], v[82:85]
	v_mfma_f32_16x16x32_bf16 v[70:73], v[200:203], v[192:195], v[70:73]
	v_mfma_f32_16x16x32_bf16 v[66:69], v[208:211], v[192:195], v[66:69]
	v_mfma_f32_16x16x32_bf16 v[118:121], v[204:207], v[168:171], v[118:121]
	s_waitcnt lgkmcnt(0)
	v_mfma_f32_16x16x32_bf16 v[114:117], v[212:215], v[168:171], v[114:117]
	v_mfma_f32_16x16x32_bf16 v[102:105], v[204:207], v[180:183], v[102:105]
	v_mfma_f32_16x16x32_bf16 v[98:101], v[212:215], v[180:183], v[98:101]
	v_mfma_f32_16x16x32_bf16 v[86:89], v[204:207], v[188:191], v[86:89]
	v_mfma_f32_16x16x32_bf16 v[82:85], v[212:215], v[188:191], v[82:85]
	v_mfma_f32_16x16x32_bf16 v[70:73], v[204:207], v[196:199], v[70:73]
	v_mfma_f32_16x16x32_bf16 v[66:69], v[212:215], v[196:199], v[66:69]
	s_setprio 0
	s_mov_b32 m0, s39
	v_lshl_add_u64 v[164:165], v[216:217], 0, s[0:1]
	s_barrier
	ds_read_b128 v[160:163], v167 offset:49152
	ds_read_b128 v[168:171], v167 offset:50176
	ds_read_b128 v[176:179], v167 offset:51200
	ds_read_b128 v[180:183], v167 offset:52224
	ds_read_b128 v[184:187], v167 offset:53248
	ds_read_b128 v[188:191], v167 offset:54272
	ds_read_b128 v[192:195], v167 offset:55296
	ds_read_b128 v[196:199], v167 offset:56320
	global_load_lds_dwordx4 v[164:165], off
	v_lshl_add_u64 v[164:165], v[218:219], 0, s[0:1]
	s_mov_b32 m0, s42
	s_nop 0
	global_load_lds_dwordx4 v[164:165], off
	s_barrier
	s_setprio 1
	s_waitcnt lgkmcnt(7)
	v_mfma_f32_16x16x32_bf16 v[62:65], v[144:147], v[160:163], v[62:65]
	v_mfma_f32_16x16x32_bf16 v[58:61], v[152:155], v[160:163], v[58:61]
	s_waitcnt lgkmcnt(5)
	v_mfma_f32_16x16x32_bf16 v[44:47], v[144:147], v[176:179], v[44:47]
	v_mfma_f32_16x16x32_bf16 v[40:43], v[152:155], v[176:179], v[40:43]
	s_waitcnt lgkmcnt(3)
	v_mfma_f32_16x16x32_bf16 v[28:31], v[144:147], v[184:187], v[28:31]
	v_mfma_f32_16x16x32_bf16 v[24:27], v[152:155], v[184:187], v[24:27]
	s_waitcnt lgkmcnt(1)
	v_mfma_f32_16x16x32_bf16 v[12:15], v[144:147], v[192:195], v[12:15]
	v_mfma_f32_16x16x32_bf16 v[8:11], v[152:155], v[192:195], v[8:11]
	v_mfma_f32_16x16x32_bf16 v[62:65], v[148:151], v[168:171], v[62:65]
	v_mfma_f32_16x16x32_bf16 v[58:61], v[156:159], v[168:171], v[58:61]
	v_mfma_f32_16x16x32_bf16 v[44:47], v[148:151], v[180:183], v[44:47]
	v_mfma_f32_16x16x32_bf16 v[40:43], v[156:159], v[180:183], v[40:43]
	v_mfma_f32_16x16x32_bf16 v[28:31], v[148:151], v[188:191], v[28:31]
	v_mfma_f32_16x16x32_bf16 v[24:27], v[156:159], v[188:191], v[24:27]
	s_waitcnt lgkmcnt(0)
	v_mfma_f32_16x16x32_bf16 v[12:15], v[148:151], v[196:199], v[12:15]
	v_mfma_f32_16x16x32_bf16 v[8:11], v[156:159], v[196:199], v[8:11]
	s_setprio 0
	s_barrier
	s_add_u32 s12, s12, 0x40080
	s_addc_u32 s13, s13, 0
	s_add_i32 s16, s16, s34
	v_lshl_add_u64 v[144:145], s[12:13], 0, v[134:135]
	s_mov_b32 m0, s16
	s_nop 0
	global_load_lds_dwordx4 v[144:145], off
	v_lshl_add_u64 v[144:145], s[12:13], 0, v[130:131]
	s_add_i32 m0, s16, 0x2000
	s_nop 0
	global_load_lds_dwordx4 v[144:145], off
	s_waitcnt vmcnt(6)
	s_barrier
	s_setprio 1
	v_mfma_f32_16x16x32_bf16 v[54:57], v[200:203], v[160:163], v[54:57]
	v_mfma_f32_16x16x32_bf16 v[50:53], v[208:211], v[160:163], v[50:53]
	v_mfma_f32_16x16x32_bf16 v[36:39], v[200:203], v[176:179], v[36:39]
	v_mfma_f32_16x16x32_bf16 v[32:35], v[208:211], v[176:179], v[32:35]
	v_mfma_f32_16x16x32_bf16 v[20:23], v[200:203], v[184:187], v[20:23]
	v_mfma_f32_16x16x32_bf16 v[16:19], v[208:211], v[184:187], v[16:19]
	v_mfma_f32_16x16x32_bf16 v[4:7], v[200:203], v[192:195], v[4:7]
	v_mfma_f32_16x16x32_bf16 v[0:3], v[208:211], v[192:195], v[0:3]
	v_mfma_f32_16x16x32_bf16 v[54:57], v[204:207], v[168:171], v[54:57]
	v_mfma_f32_16x16x32_bf16 v[50:53], v[212:215], v[168:171], v[50:53]
	v_mfma_f32_16x16x32_bf16 v[36:39], v[204:207], v[180:183], v[36:39]
	v_mfma_f32_16x16x32_bf16 v[32:35], v[212:215], v[180:183], v[32:35]
	v_mfma_f32_16x16x32_bf16 v[20:23], v[204:207], v[188:191], v[20:23]
	v_mfma_f32_16x16x32_bf16 v[16:19], v[212:215], v[188:191], v[16:19]
	v_mfma_f32_16x16x32_bf16 v[4:7], v[204:207], v[196:199], v[4:7]
	v_mfma_f32_16x16x32_bf16 v[0:3], v[212:215], v[196:199], v[0:3]
	s_setprio 0
	s_add_i32 s56, s56, 2
	s_add_u32 s6, s6, 0x100
	s_addc_u32 s7, s7, 0
	s_add_u32 s54, s54, 0x100
	s_addc_u32 s55, s55, 0
	s_cmp_gt_u32 s56, 13
	s_barrier
	s_cbranch_scc0 .LBB0_335
	s_cmp_gt_i32 s49, 3
	s_cselect_b64 s[6:7], -1, 0
	s_and_b64 s[12:13], s[6:7], exec
	s_mov_b32 s12, 0xfe00000
	s_cselect_b32 s12, s12, 0xba00000
	v_mov_b32_e32 v48, 0x3e38aa3b
	v_cndmask_b32_e64 v48, v48, 1.0, s[6:7]
	s_cselect_b32 s6, s46, s44
	s_cselect_b32 s7, s47, s45
	s_add_u32 s12, s8, s12
	s_addc_u32 s13, s9, 0
	s_add_u32 s6, s6, s10
	s_addc_u32 s7, s7, s11
	v_lshlrev_b32_e32 v156, 2, v138
	global_load_dwordx4 v[152:155], v156, s[6:7] offset:16
	global_load_dwordx4 v[144:147], v156, s[6:7]
	v_pk_mul_f32 v[170:171], v[126:127], v[126:127]
	v_mul_f32_e32 v169, v115, v115
	v_mul_f32_e32 v175, v117, v117
	s_waitcnt vmcnt(0)
	v_pk_mul_f32 v[148:149], v[48:49], v[146:147] op_sel_hi:[0,1]
	v_pk_mul_f32 v[150:151], v[48:49], v[144:145] op_sel_hi:[0,1]
	v_pk_mul_f32 v[144:145], v[48:49], v[154:155] op_sel_hi:[0,1]
	v_pk_mul_f32 v[146:147], v[48:49], v[152:153] op_sel_hi:[0,1]
	global_load_dwordx4 v[160:163], v156, s[6:7] offset:144
	global_load_dwordx4 v[152:155], v156, s[6:7] offset:128
	s_waitcnt vmcnt(0)
	v_pk_mul_f32 v[156:157], v[48:49], v[154:155] op_sel_hi:[0,1]
	v_pk_mul_f32 v[154:155], v[48:49], v[160:161] op_sel_hi:[0,1]
	v_pk_mul_f32 v[160:161], v[128:129], v[128:129]
	v_pk_mul_f32 v[158:159], v[48:49], v[152:153] op_sel_hi:[0,1]
	v_pk_mov_b32 v[172:173], v[170:171], v[160:161] op_sel:[1,0]
	v_mov_b32_e32 v171, v161
	v_pk_add_f32 v[160:161], v[172:173], v[170:171]
	v_pk_mul_f32 v[170:171], v[124:125], v[124:125]
	v_pk_mul_f32 v[172:173], v[122:123], v[122:123]
	v_pk_mul_f32 v[152:153], v[48:49], v[162:163] op_sel_hi:[0,1]
	v_pk_mov_b32 v[176:177], v[172:173], v[170:171] op_sel:[1,0]
	v_mov_b32_e32 v173, v171
	v_pk_add_f32 v[170:171], v[176:177], v[172:173]
	v_lshl_add_u32 v162, s2, 8, v139
	s_lshl_b32 s2, s49, 9
	v_mul_f32_e32 v163, v114, v114
	v_pk_add_f32 v[160:161], v[160:161], v[160:161] op_sel:[0,1] op_sel_hi:[1,0]
	v_pk_add_f32 v[170:171], v[170:171], v[170:171] op_sel:[0,1] op_sel_hi:[1,0]
	s_and_b32 s2, s2, 0x600
	v_mov_b32_e32 v161, v163
	v_mov_b32_e32 v171, v169
	s_add_u32 s2, s12, s2
	v_pk_add_f32 v[160:161], v[160:161], v[170:171]
	v_mul_f32_e32 v170, v119, v119
	s_addc_u32 s7, s13, 0
	v_mul_f32_e32 v172, v116, v116
	v_pk_fma_f32 v[170:171], v[118:119], v[118:119], v[170:171] op_sel_hi:[1,1,0]
	s_add_u32 s6, s2, s48
	v_mov_b32_e32 v171, v172
	v_mul_f32_e32 v172, v121, v121
	s_addc_u32 s7, s7, 0
	v_lshlrev_b32_e32 v48, 1, v138
	v_pk_fma_f32 v[172:173], v[120:121], v[120:121], v[172:173] op_sel_hi:[1,1,0]
	v_lshl_add_u64 v[164:165], s[6:7], 0, v[48:49]
	v_xor_b32_e32 v48, 16, v222
	v_mov_b32_e32 v173, v175
	v_cmp_lt_i32_e32 vcc, v48, v227
	v_pk_add_f32 v[170:171], v[170:171], v[172:173]
	v_ashrrev_i32_e32 v163, 31, v162
	v_cndmask_b32_e32 v48, v222, v48, vcc
	v_pk_add_f32 v[160:161], v[160:161], v[170:171]
	v_lshlrev_b32_e32 v168, 2, v48
	v_add_f32_e32 v160, v160, v161
	ds_bpermute_b32 v161, v168, v160
	v_cmp_lt_i32_e32 vcc, v226, v227
	s_mov_b32 s2, 0x40000
	s_mov_b64 s[6:7], 0x40000
	v_cndmask_b32_e32 v48, v222, v226, vcc
	v_lshlrev_b32_e32 v48, 2, v48
	s_waitcnt lgkmcnt(0)
	v_add_f32_e32 v160, v160, v161
	ds_bpermute_b32 v161, v48, v160
	s_mov_b32 s49, s20
	s_mov_b64 s[12:13], s[26:27]
	s_waitcnt lgkmcnt(0)
	v_add_f32_e32 v160, v160, v161
	v_fmamk_f32 v160, v160, 0x3c800000, v223
	v_rsq_f32_e32 v170, v160
	v_lshlrev_b64 v[160:161], 11, v[162:163]
	v_lshl_add_u64 v[160:161], v[164:165], 0, v[160:161]
	v_pk_mul_f32 v[126:127], v[126:127], v[170:171] op_sel_hi:[1,0]
	v_pk_mul_f32 v[128:129], v[128:129], v[170:171] op_sel_hi:[1,0]
	v_pk_mul_f32 v[122:123], v[122:123], v[170:171] op_sel_hi:[1,0]
	v_pk_mul_f32 v[124:125], v[124:125], v[170:171] op_sel_hi:[1,0]
	v_pk_mul_f32 v[128:129], v[148:149], v[128:129]
	v_pk_mul_f32 v[126:127], v[150:151], v[126:127]
	v_pk_mul_f32 v[172:173], v[144:145], v[124:125]
	v_pk_mul_f32 v[124:125], v[146:147], v[122:123]
	v_cvt_pk_bf16_f32 v122, v126, v127
	v_cvt_pk_bf16_f32 v123, v128, v129
	v_pk_mul_f32 v[114:115], v[114:115], v[170:171] op_sel_hi:[1,0]
	v_pk_mul_f32 v[116:117], v[116:117], v[170:171] op_sel_hi:[1,0]
	v_cvt_pk_bf16_f32 v124, v124, v125
	v_cvt_pk_bf16_f32 v125, v172, v173
	global_store_dwordx4 v[160:161], v[122:125], off
	v_pk_mul_f32 v[118:119], v[118:119], v[170:171] op_sel_hi:[1,0]
	v_pk_mul_f32 v[120:121], v[120:121], v[170:171] op_sel_hi:[1,0]
	v_pk_mul_f32 v[122:123], v[152:153], v[116:117]
	v_pk_mul_f32 v[116:117], v[154:155], v[114:115]
	v_pk_mul_f32 v[120:121], v[156:157], v[120:121]
	v_pk_mul_f32 v[118:119], v[158:159], v[118:119]
	s_nop 0
	v_cvt_pk_bf16_f32 v114, v118, v119
	v_cvt_pk_bf16_f32 v115, v120, v121
	v_cvt_pk_bf16_f32 v116, v116, v117
	v_cvt_pk_bf16_f32 v117, v122, v123
	global_store_dwordx4 v[160:161], v[114:117], off offset:64
	s_nop 1
	v_pk_mul_f32 v[114:115], v[112:113], v[112:113]
	v_pk_mul_f32 v[116:117], v[110:111], v[110:111]
	s_nop 0
	v_pk_mov_b32 v[118:119], v[116:117], v[114:115] op_sel:[1,0]
	v_mov_b32_e32 v117, v115
	v_pk_add_f32 v[114:115], v[118:119], v[116:117]
	v_pk_mul_f32 v[116:117], v[108:109], v[108:109]
	v_pk_mul_f32 v[118:119], v[106:107], v[106:107]
	v_pk_add_f32 v[114:115], v[114:115], v[114:115] op_sel:[0,1] op_sel_hi:[1,0]
	v_pk_mov_b32 v[120:121], v[118:119], v[116:117] op_sel:[1,0]
	v_mov_b32_e32 v119, v117
	v_pk_add_f32 v[116:117], v[120:121], v[118:119]
	v_mul_f32_e32 v118, v98, v98
	v_mul_f32_e32 v119, v99, v99
	v_pk_add_f32 v[116:117], v[116:117], v[116:117] op_sel:[0,1] op_sel_hi:[1,0]
	v_mov_b32_e32 v115, v118
	v_mov_b32_e32 v117, v119
	v_pk_add_f32 v[114:115], v[114:115], v[116:117]
	v_mul_f32_e32 v116, v103, v103
	v_mul_f32_e32 v118, v105, v105
	v_mul_f32_e32 v120, v100, v100
	v_mul_f32_e32 v121, v101, v101
	v_pk_fma_f32 v[116:117], v[102:103], v[102:103], v[116:117] op_sel_hi:[1,1,0]
	v_pk_fma_f32 v[118:119], v[104:105], v[104:105], v[118:119] op_sel_hi:[1,1,0]
	v_mov_b32_e32 v117, v120
	v_mov_b32_e32 v119, v121
	v_pk_add_f32 v[116:117], v[116:117], v[118:119]
	s_nop 0
	v_pk_add_f32 v[114:115], v[114:115], v[116:117]
	v_or_b32_e32 v116, 16, v162
	v_add_f32_e32 v114, v114, v115
	ds_bpermute_b32 v115, v168, v114
	v_ashrrev_i32_e32 v117, 31, v116
	v_lshlrev_b64 v[116:117], 11, v[116:117]
	v_lshl_add_u64 v[116:117], v[164:165], 0, v[116:117]
	s_waitcnt lgkmcnt(0)
	v_add_f32_e32 v114, v114, v115
	ds_bpermute_b32 v115, v48, v114
	s_waitcnt lgkmcnt(0)
	v_add_f32_e32 v114, v114, v115
	v_fmamk_f32 v114, v114, 0x3c800000, v223
	v_rsq_f32_e32 v114, v114
	s_nop 0
	v_pk_mul_f32 v[110:111], v[110:111], v[114:115] op_sel_hi:[1,0]
	v_pk_mul_f32 v[112:113], v[112:113], v[114:115] op_sel_hi:[1,0]
	v_pk_mul_f32 v[106:107], v[106:107], v[114:115] op_sel_hi:[1,0]
	v_pk_mul_f32 v[108:109], v[108:109], v[114:115] op_sel_hi:[1,0]
	v_pk_mul_f32 v[112:113], v[148:149], v[112:113]
	v_pk_mul_f32 v[110:111], v[150:151], v[110:111]
	v_pk_mul_f32 v[118:119], v[144:145], v[108:109]
	v_pk_mul_f32 v[108:109], v[146:147], v[106:107]
	v_cvt_pk_bf16_f32 v106, v110, v111
	v_cvt_pk_bf16_f32 v107, v112, v113
	v_pk_mul_f32 v[98:99], v[98:99], v[114:115] op_sel_hi:[1,0]
	v_pk_mul_f32 v[100:101], v[100:101], v[114:115] op_sel_hi:[1,0]
	v_cvt_pk_bf16_f32 v108, v108, v109
	v_cvt_pk_bf16_f32 v109, v118, v119
	global_store_dwordx4 v[116:117], v[106:109], off
	v_pk_mul_f32 v[102:103], v[102:103], v[114:115] op_sel_hi:[1,0]
	v_pk_mul_f32 v[104:105], v[104:105], v[114:115] op_sel_hi:[1,0]
	v_pk_mul_f32 v[106:107], v[152:153], v[100:101]
	v_pk_mul_f32 v[100:101], v[154:155], v[98:99]
	v_pk_mul_f32 v[104:105], v[156:157], v[104:105]
	v_pk_mul_f32 v[102:103], v[158:159], v[102:103]
	s_nop 0
	v_cvt_pk_bf16_f32 v98, v102, v103
	v_cvt_pk_bf16_f32 v99, v104, v105
	v_cvt_pk_bf16_f32 v100, v100, v101
	v_cvt_pk_bf16_f32 v101, v106, v107
	global_store_dwordx4 v[116:117], v[98:101], off offset:64
	s_nop 1
	v_pk_mul_f32 v[98:99], v[96:97], v[96:97]
	v_pk_mul_f32 v[100:101], v[94:95], v[94:95]
	s_nop 0
	v_pk_mov_b32 v[102:103], v[100:101], v[98:99] op_sel:[1,0]
	v_mov_b32_e32 v101, v99
	v_pk_add_f32 v[98:99], v[102:103], v[100:101]
	v_pk_mul_f32 v[100:101], v[92:93], v[92:93]
	v_pk_mul_f32 v[102:103], v[90:91], v[90:91]
	v_pk_add_f32 v[98:99], v[98:99], v[98:99] op_sel:[0,1] op_sel_hi:[1,0]
	v_pk_mov_b32 v[104:105], v[102:103], v[100:101] op_sel:[1,0]
	v_mov_b32_e32 v103, v101
	v_pk_add_f32 v[100:101], v[104:105], v[102:103]
	v_mul_f32_e32 v102, v82, v82
	v_mul_f32_e32 v103, v83, v83
	v_pk_add_f32 v[100:101], v[100:101], v[100:101] op_sel:[0,1] op_sel_hi:[1,0]
	v_mov_b32_e32 v99, v102
	v_mov_b32_e32 v101, v103
	v_pk_add_f32 v[98:99], v[98:99], v[100:101]
	v_mul_f32_e32 v100, v87, v87
	v_mul_f32_e32 v102, v89, v89
	v_mul_f32_e32 v104, v84, v84
	v_mul_f32_e32 v105, v85, v85
	v_pk_fma_f32 v[100:101], v[86:87], v[86:87], v[100:101] op_sel_hi:[1,1,0]
	v_pk_fma_f32 v[102:103], v[88:89], v[88:89], v[102:103] op_sel_hi:[1,1,0]
	v_mov_b32_e32 v101, v104
	v_mov_b32_e32 v103, v105
	v_pk_add_f32 v[100:101], v[100:101], v[102:103]
	s_nop 0
	v_pk_add_f32 v[98:99], v[98:99], v[100:101]
	v_or_b32_e32 v100, 32, v162
	v_add_f32_e32 v98, v98, v99
	ds_bpermute_b32 v99, v168, v98
	v_ashrrev_i32_e32 v101, 31, v100
	v_lshlrev_b64 v[100:101], 11, v[100:101]
	v_lshl_add_u64 v[100:101], v[164:165], 0, v[100:101]
	s_waitcnt lgkmcnt(0)
	v_add_f32_e32 v98, v98, v99
	ds_bpermute_b32 v99, v48, v98
	s_waitcnt lgkmcnt(0)
	v_add_f32_e32 v98, v98, v99
	v_fmamk_f32 v98, v98, 0x3c800000, v223
	v_rsq_f32_e32 v98, v98
	s_nop 0
	v_pk_mul_f32 v[94:95], v[94:95], v[98:99] op_sel_hi:[1,0]
	v_pk_mul_f32 v[96:97], v[96:97], v[98:99] op_sel_hi:[1,0]
	v_pk_mul_f32 v[90:91], v[90:91], v[98:99] op_sel_hi:[1,0]
	v_pk_mul_f32 v[92:93], v[92:93], v[98:99] op_sel_hi:[1,0]
	v_pk_mul_f32 v[96:97], v[148:149], v[96:97]
	v_pk_mul_f32 v[94:95], v[150:151], v[94:95]
	v_pk_mul_f32 v[102:103], v[144:145], v[92:93]
	v_pk_mul_f32 v[92:93], v[146:147], v[90:91]
	v_cvt_pk_bf16_f32 v90, v94, v95
	v_cvt_pk_bf16_f32 v91, v96, v97
	v_pk_mul_f32 v[82:83], v[82:83], v[98:99] op_sel_hi:[1,0]
	v_pk_mul_f32 v[84:85], v[84:85], v[98:99] op_sel_hi:[1,0]
	v_cvt_pk_bf16_f32 v92, v92, v93
	v_cvt_pk_bf16_f32 v93, v102, v103
	global_store_dwordx4 v[100:101], v[90:93], off
	v_pk_mul_f32 v[86:87], v[86:87], v[98:99] op_sel_hi:[1,0]
	v_pk_mul_f32 v[88:89], v[88:89], v[98:99] op_sel_hi:[1,0]
	v_pk_mul_f32 v[90:91], v[152:153], v[84:85]
	v_pk_mul_f32 v[84:85], v[154:155], v[82:83]
	v_pk_mul_f32 v[88:89], v[156:157], v[88:89]
	v_pk_mul_f32 v[86:87], v[158:159], v[86:87]
	s_nop 0
	v_cvt_pk_bf16_f32 v82, v86, v87
	v_cvt_pk_bf16_f32 v83, v88, v89
	v_cvt_pk_bf16_f32 v84, v84, v85
	v_cvt_pk_bf16_f32 v85, v90, v91
	global_store_dwordx4 v[100:101], v[82:85], off offset:64
	s_nop 1
	v_pk_mul_f32 v[82:83], v[80:81], v[80:81]
	v_pk_mul_f32 v[84:85], v[78:79], v[78:79]
	s_nop 0
	v_pk_mov_b32 v[86:87], v[84:85], v[82:83] op_sel:[1,0]
	v_mov_b32_e32 v85, v83
	v_pk_add_f32 v[82:83], v[86:87], v[84:85]
	v_pk_mul_f32 v[84:85], v[76:77], v[76:77]
	v_pk_mul_f32 v[86:87], v[74:75], v[74:75]
	v_pk_add_f32 v[82:83], v[82:83], v[82:83] op_sel:[0,1] op_sel_hi:[1,0]
	v_pk_mov_b32 v[88:89], v[86:87], v[84:85] op_sel:[1,0]
	v_mov_b32_e32 v87, v85
	v_pk_add_f32 v[84:85], v[88:89], v[86:87]
	v_mul_f32_e32 v86, v66, v66
	v_mul_f32_e32 v87, v67, v67
	v_pk_add_f32 v[84:85], v[84:85], v[84:85] op_sel:[0,1] op_sel_hi:[1,0]
	v_mov_b32_e32 v83, v86
	v_mov_b32_e32 v85, v87
	v_pk_add_f32 v[82:83], v[82:83], v[84:85]
	v_mul_f32_e32 v84, v71, v71
	v_mul_f32_e32 v86, v73, v73
	v_mul_f32_e32 v88, v68, v68
	v_mul_f32_e32 v89, v69, v69
	v_pk_fma_f32 v[84:85], v[70:71], v[70:71], v[84:85] op_sel_hi:[1,1,0]
	v_pk_fma_f32 v[86:87], v[72:73], v[72:73], v[86:87] op_sel_hi:[1,1,0]
	v_mov_b32_e32 v85, v88
	v_mov_b32_e32 v87, v89
	v_pk_add_f32 v[84:85], v[84:85], v[86:87]
	s_nop 0
	v_pk_add_f32 v[82:83], v[82:83], v[84:85]
	v_or_b32_e32 v84, 48, v162
	v_add_f32_e32 v82, v82, v83
	ds_bpermute_b32 v83, v168, v82
	v_ashrrev_i32_e32 v85, 31, v84
	v_lshlrev_b64 v[84:85], 11, v[84:85]
	v_lshl_add_u64 v[84:85], v[164:165], 0, v[84:85]
	s_waitcnt lgkmcnt(0)
	v_add_f32_e32 v82, v82, v83
	ds_bpermute_b32 v83, v48, v82
	s_waitcnt lgkmcnt(0)
	v_add_f32_e32 v82, v82, v83
	v_fmamk_f32 v82, v82, 0x3c800000, v223
	v_rsq_f32_e32 v82, v82
	s_nop 0
	v_pk_mul_f32 v[78:79], v[78:79], v[82:83] op_sel_hi:[1,0]
	v_pk_mul_f32 v[80:81], v[80:81], v[82:83] op_sel_hi:[1,0]
	v_pk_mul_f32 v[74:75], v[74:75], v[82:83] op_sel_hi:[1,0]
	v_pk_mul_f32 v[76:77], v[76:77], v[82:83] op_sel_hi:[1,0]
	v_pk_mul_f32 v[80:81], v[148:149], v[80:81]
	v_pk_mul_f32 v[78:79], v[150:151], v[78:79]
	v_pk_mul_f32 v[86:87], v[144:145], v[76:77]
	v_pk_mul_f32 v[76:77], v[146:147], v[74:75]
	v_cvt_pk_bf16_f32 v74, v78, v79
	v_cvt_pk_bf16_f32 v75, v80, v81
	v_pk_mul_f32 v[66:67], v[66:67], v[82:83] op_sel_hi:[1,0]
	v_pk_mul_f32 v[68:69], v[68:69], v[82:83] op_sel_hi:[1,0]
	v_cvt_pk_bf16_f32 v76, v76, v77
	v_cvt_pk_bf16_f32 v77, v86, v87
	global_store_dwordx4 v[84:85], v[74:77], off
	v_pk_mul_f32 v[70:71], v[70:71], v[82:83] op_sel_hi:[1,0]
	v_pk_mul_f32 v[72:73], v[72:73], v[82:83] op_sel_hi:[1,0]
	v_pk_mul_f32 v[74:75], v[152:153], v[68:69]
	v_pk_mul_f32 v[68:69], v[154:155], v[66:67]
	v_pk_mul_f32 v[72:73], v[156:157], v[72:73]
	v_pk_mul_f32 v[70:71], v[158:159], v[70:71]
	s_nop 0
	v_cvt_pk_bf16_f32 v66, v70, v71
	v_cvt_pk_bf16_f32 v67, v72, v73
	v_cvt_pk_bf16_f32 v68, v68, v69
	v_cvt_pk_bf16_f32 v69, v74, v75
	global_store_dwordx4 v[84:85], v[66:69], off offset:64
	s_nop 1
	v_pk_mul_f32 v[66:67], v[64:65], v[64:65]
	v_pk_mul_f32 v[68:69], v[62:63], v[62:63]
	s_nop 0
	v_pk_mov_b32 v[70:71], v[68:69], v[66:67] op_sel:[1,0]
	v_mov_b32_e32 v69, v67
	v_pk_add_f32 v[66:67], v[70:71], v[68:69]
	v_pk_mul_f32 v[68:69], v[60:61], v[60:61]
	v_pk_mul_f32 v[70:71], v[58:59], v[58:59]
	v_pk_add_f32 v[66:67], v[66:67], v[66:67] op_sel:[0,1] op_sel_hi:[1,0]
	v_pk_mov_b32 v[72:73], v[70:71], v[68:69] op_sel:[1,0]
	v_mov_b32_e32 v71, v69
	v_pk_add_f32 v[68:69], v[72:73], v[70:71]
	v_mul_f32_e32 v70, v50, v50
	v_mul_f32_e32 v71, v51, v51
	v_pk_add_f32 v[68:69], v[68:69], v[68:69] op_sel:[0,1] op_sel_hi:[1,0]
	v_mov_b32_e32 v67, v70
	v_mov_b32_e32 v69, v71
	v_pk_add_f32 v[66:67], v[66:67], v[68:69]
	v_mul_f32_e32 v68, v55, v55
	v_mul_f32_e32 v70, v57, v57
	v_mul_f32_e32 v72, v52, v52
	v_mul_f32_e32 v73, v53, v53
	v_pk_fma_f32 v[68:69], v[54:55], v[54:55], v[68:69] op_sel_hi:[1,1,0]
	v_pk_fma_f32 v[70:71], v[56:57], v[56:57], v[70:71] op_sel_hi:[1,1,0]
	v_mov_b32_e32 v69, v72
	v_mov_b32_e32 v71, v73
	v_pk_add_f32 v[68:69], v[68:69], v[70:71]
	s_nop 0
	v_pk_add_f32 v[66:67], v[66:67], v[68:69]
	v_lshl_add_u64 v[68:69], v[160:161], 0, s[6:7]
	v_add_f32_e32 v66, v66, v67
	ds_bpermute_b32 v67, v168, v66
	s_mov_b64 s[6:7], 0x48000
	s_waitcnt lgkmcnt(0)
	v_add_f32_e32 v66, v66, v67
	ds_bpermute_b32 v67, v48, v66
	s_waitcnt lgkmcnt(0)
	v_add_f32_e32 v66, v66, v67
	v_fmamk_f32 v66, v66, 0x3c800000, v223
	v_rsq_f32_e32 v66, v66
	s_nop 0
	v_pk_mul_f32 v[62:63], v[62:63], v[66:67] op_sel_hi:[1,0]
	s_nop 0
	v_pk_mul_f32 v[62:63], v[150:151], v[62:63]
	v_pk_mul_f32 v[58:59], v[58:59], v[66:67] op_sel_hi:[1,0]
	v_pk_mul_f32 v[60:61], v[60:61], v[66:67] op_sel_hi:[1,0]
	v_pk_mul_f32 v[64:65], v[64:65], v[66:67] op_sel_hi:[1,0]
	v_pk_mul_f32 v[70:71], v[144:145], v[60:61]
	v_pk_mul_f32 v[60:61], v[146:147], v[58:59]
	v_cvt_pk_bf16_f32 v58, v62, v63
	v_add_co_u32_e32 v62, vcc, s2, v160
	v_pk_mul_f32 v[64:65], v[148:149], v[64:65]
	s_nop 0
	v_addc_co_u32_e32 v63, vcc, 0, v161, vcc
	v_cvt_pk_bf16_f32 v59, v64, v65
	v_pk_mul_f32 v[50:51], v[50:51], v[66:67] op_sel_hi:[1,0]
	v_pk_mul_f32 v[52:53], v[52:53], v[66:67] op_sel_hi:[1,0]
	v_cvt_pk_bf16_f32 v60, v60, v61
	v_cvt_pk_bf16_f32 v61, v70, v71
	global_store_dwordx4 v[62:63], v[58:61], off
	v_pk_mul_f32 v[54:55], v[54:55], v[66:67] op_sel_hi:[1,0]
	v_pk_mul_f32 v[56:57], v[56:57], v[66:67] op_sel_hi:[1,0]
	v_pk_mul_f32 v[58:59], v[152:153], v[52:53]
	v_pk_mul_f32 v[52:53], v[154:155], v[50:51]
	v_pk_mul_f32 v[56:57], v[156:157], v[56:57]
	v_pk_mul_f32 v[54:55], v[158:159], v[54:55]
	s_mov_b32 s2, 0x50000
	v_cvt_pk_bf16_f32 v50, v54, v55
	v_cvt_pk_bf16_f32 v51, v56, v57
	v_cvt_pk_bf16_f32 v52, v52, v53
	v_cvt_pk_bf16_f32 v53, v58, v59
	global_store_dwordx4 v[68:69], v[50:53], off offset:64
	s_nop 1
	v_pk_mul_f32 v[50:51], v[46:47], v[46:47]
	v_pk_mul_f32 v[52:53], v[44:45], v[44:45]
	s_nop 0
	v_pk_mov_b32 v[54:55], v[52:53], v[50:51] op_sel:[1,0]
	v_mov_b32_e32 v53, v51
	v_pk_add_f32 v[50:51], v[54:55], v[52:53]
	v_pk_mul_f32 v[52:53], v[42:43], v[42:43]
	v_pk_mul_f32 v[54:55], v[40:41], v[40:41]
	v_pk_add_f32 v[50:51], v[50:51], v[50:51] op_sel:[0,1] op_sel_hi:[1,0]
	v_pk_mov_b32 v[56:57], v[54:55], v[52:53] op_sel:[1,0]
	v_mov_b32_e32 v55, v53
	v_pk_add_f32 v[52:53], v[56:57], v[54:55]
	v_mul_f32_e32 v54, v32, v32
	v_mul_f32_e32 v55, v33, v33
	v_pk_add_f32 v[52:53], v[52:53], v[52:53] op_sel:[0,1] op_sel_hi:[1,0]
	v_mov_b32_e32 v51, v54
	v_mov_b32_e32 v53, v55
	v_pk_add_f32 v[50:51], v[50:51], v[52:53]
	v_mul_f32_e32 v52, v37, v37
	v_mul_f32_e32 v54, v39, v39
	v_mul_f32_e32 v56, v34, v34
	v_mul_f32_e32 v57, v35, v35
	v_pk_fma_f32 v[52:53], v[36:37], v[36:37], v[52:53] op_sel_hi:[1,1,0]
	v_pk_fma_f32 v[54:55], v[38:39], v[38:39], v[54:55] op_sel_hi:[1,1,0]
	v_mov_b32_e32 v53, v56
	v_mov_b32_e32 v55, v57
	v_pk_add_f32 v[52:53], v[52:53], v[54:55]
	s_nop 0
	v_pk_add_f32 v[50:51], v[50:51], v[52:53]
	v_lshl_add_u64 v[52:53], v[160:161], 0, s[6:7]
	v_add_f32_e32 v50, v50, v51
	ds_bpermute_b32 v51, v168, v50
	s_mov_b64 s[6:7], 0x50000
	s_waitcnt lgkmcnt(0)
	v_add_f32_e32 v50, v50, v51
	ds_bpermute_b32 v51, v48, v50
	s_waitcnt lgkmcnt(0)
	v_add_f32_e32 v50, v50, v51
	v_fmamk_f32 v50, v50, 0x3c800000, v223
	v_rsq_f32_e32 v50, v50
	s_nop 0
	v_pk_mul_f32 v[44:45], v[44:45], v[50:51] op_sel_hi:[1,0]
	s_nop 0
	v_pk_mul_f32 v[44:45], v[150:151], v[44:45]
	v_pk_mul_f32 v[40:41], v[40:41], v[50:51] op_sel_hi:[1,0]
	v_pk_mul_f32 v[42:43], v[42:43], v[50:51] op_sel_hi:[1,0]
	v_pk_mul_f32 v[46:47], v[46:47], v[50:51] op_sel_hi:[1,0]
	v_pk_mul_f32 v[54:55], v[144:145], v[42:43]
	v_pk_mul_f32 v[42:43], v[146:147], v[40:41]
	v_cvt_pk_bf16_f32 v40, v44, v45
	v_add_co_u32_e32 v44, vcc, s58, v160
	v_pk_mul_f32 v[46:47], v[148:149], v[46:47]
	s_nop 0
	v_addc_co_u32_e32 v45, vcc, 0, v161, vcc
	v_cvt_pk_bf16_f32 v41, v46, v47
	v_pk_mul_f32 v[32:33], v[32:33], v[50:51] op_sel_hi:[1,0]
	v_pk_mul_f32 v[34:35], v[34:35], v[50:51] op_sel_hi:[1,0]
	v_cvt_pk_bf16_f32 v42, v42, v43
	v_cvt_pk_bf16_f32 v43, v54, v55
	global_store_dwordx4 v[44:45], v[40:43], off
	v_pk_mul_f32 v[36:37], v[36:37], v[50:51] op_sel_hi:[1,0]
	v_pk_mul_f32 v[38:39], v[38:39], v[50:51] op_sel_hi:[1,0]
	v_pk_mul_f32 v[40:41], v[152:153], v[34:35]
	v_pk_mul_f32 v[34:35], v[154:155], v[32:33]
	v_pk_mul_f32 v[38:39], v[156:157], v[38:39]
	v_pk_mul_f32 v[36:37], v[158:159], v[36:37]
	s_nop 0
	v_cvt_pk_bf16_f32 v32, v36, v37
	v_cvt_pk_bf16_f32 v33, v38, v39
	v_cvt_pk_bf16_f32 v34, v34, v35
	v_cvt_pk_bf16_f32 v35, v40, v41
	global_store_dwordx4 v[52:53], v[32:35], off offset:64
	s_nop 1
	v_pk_mul_f32 v[32:33], v[30:31], v[30:31]
	v_pk_mul_f32 v[34:35], v[28:29], v[28:29]
	s_nop 0
	v_pk_mov_b32 v[36:37], v[34:35], v[32:33] op_sel:[1,0]
	v_mov_b32_e32 v35, v33
	v_pk_add_f32 v[32:33], v[36:37], v[34:35]
	v_pk_mul_f32 v[34:35], v[26:27], v[26:27]
	v_pk_mul_f32 v[36:37], v[24:25], v[24:25]
	v_pk_add_f32 v[32:33], v[32:33], v[32:33] op_sel:[0,1] op_sel_hi:[1,0]
	v_pk_mov_b32 v[38:39], v[36:37], v[34:35] op_sel:[1,0]
	v_mov_b32_e32 v37, v35
	v_pk_add_f32 v[34:35], v[38:39], v[36:37]
	v_mul_f32_e32 v36, v16, v16
	v_mul_f32_e32 v37, v17, v17
	v_pk_add_f32 v[34:35], v[34:35], v[34:35] op_sel:[0,1] op_sel_hi:[1,0]
	v_mov_b32_e32 v33, v36
	v_mov_b32_e32 v35, v37
	v_pk_add_f32 v[32:33], v[32:33], v[34:35]
	v_mul_f32_e32 v34, v21, v21
	v_mul_f32_e32 v36, v23, v23
	v_mul_f32_e32 v38, v18, v18
	v_mul_f32_e32 v39, v19, v19
	v_pk_fma_f32 v[34:35], v[20:21], v[20:21], v[34:35] op_sel_hi:[1,1,0]
	v_pk_fma_f32 v[36:37], v[22:23], v[22:23], v[36:37] op_sel_hi:[1,1,0]
	v_mov_b32_e32 v35, v38
	v_mov_b32_e32 v37, v39
	v_pk_add_f32 v[34:35], v[34:35], v[36:37]
	s_nop 0
	v_pk_add_f32 v[32:33], v[32:33], v[34:35]
	v_lshl_add_u64 v[34:35], v[160:161], 0, s[6:7]
	v_add_f32_e32 v32, v32, v33
	ds_bpermute_b32 v33, v168, v32
	s_mov_b64 s[6:7], 0x58000
	s_waitcnt lgkmcnt(0)
; __device__ __forceinline__ unsigned cvt_pk_bf16(float lo, float hi) { unsigned r; asm volatile("v_cvt_pk_bf16_f32 %0, %1, %2" : "=v"(r) : "v"(lo), "v"(hi)); return r; }
; #define PG8_WAIT_V(n) asm volatile("s_waitcnt vmcnt(" #n ")" ::: "memory")
; #define PG8_BAR __builtin_amdgcn_s_barrier()
; template <class Epi, class Sched>
; __device__ __forceinline__ void gemm_phase(PG8_LAS unsigned char* lds, const Gemm g, const Sched& S, const Epi& E) {
;     ...
;         if constexpr (!Epi::AFTER_DRAIN) { E(acc, cur, wr, wc, fr, fq); S.done(cur); }
;         if (!has_next) break;
; #pragma unroll
;         for (int a = 0; a < 2; ++a)
; #pragma unroll
;             for (int b = 0; b < 2; ++b)
; #pragma unroll
;                 for (int m = 0; m < 4; ++m)
; #pragma unroll
;                     for (int n = 0; n < 2; ++n) acc[a][b][m][n] = (f32x4){0.f, 0.f, 0.f, 0.f};
;         cur = nxt; cA = nA; cB = nB; ++ui;
;     }
;     PG8_WAIT_V(0);
;     if (wr == 0) PG8_BAR;
;     PG8_BAR;
;     __device__ __forceinline__ void operator()(const f32x4 (&acc)[2][2][4][2], const pg8::Unit& u, int wr, int wc, int fr, int fq) const {
;     ...
;                 float ss = 0.f;
; #pragma unroll
;                 for (int bj = 0; bj < 2; ++bj)
; #pragma unroll
;                     for (int n = 0; n < 2; ++n) { const f32x4 x = acc[ai][bj][m][n]; ss += (x[0] * x[0] + x[1] * x[1]) + (x[2] * x[2] + x[3] * x[3]); }
;                 ss += __shfl_xor(ss, 16); ss += __shfl_xor(ss, 32);
;                 const float rs = __builtin_amdgcn_rsqf(ss * (1.0f / 64.0f) + EPSN);
;                 bf16_t* rowp = base + (size_t)(row0 + ai * 128 + m * 16) * DM;
; #pragma unroll
;                 for (int bj = 0; bj < 2; ++bj) { const f32x4 v0 = acc[ai][bj][m][0] * rs * gv[bj][0], v1 = acc[ai][bj][m][1] * rs * gv[bj][1];
;                     u32x4 w; w.x = pg8::cvt_pk_bf16(v0[0], v0[1]); w.y = pg8::cvt_pk_bf16(v0[2], v0[3]); w.z = pg8::cvt_pk_bf16(v1[0], v1[1]); w.w = pg8::cvt_pk_bf16(v1[2], v1[3]);
;                     *(u32x4*)(rowp + 32 * bj) = w; }
	v_add_f32_e32 v32, v32, v33
	ds_bpermute_b32 v33, v48, v32
	s_waitcnt lgkmcnt(0)
	v_add_f32_e32 v32, v32, v33
	v_fmamk_f32 v32, v32, 0x3c800000, v223
	v_rsq_f32_e32 v32, v32
	s_nop 0
	v_pk_mul_f32 v[28:29], v[28:29], v[32:33] op_sel_hi:[1,0]
	s_nop 0
	v_pk_mul_f32 v[28:29], v[150:151], v[28:29]
	v_pk_mul_f32 v[24:25], v[24:25], v[32:33] op_sel_hi:[1,0]
	v_pk_mul_f32 v[26:27], v[26:27], v[32:33] op_sel_hi:[1,0]
	v_pk_mul_f32 v[30:31], v[30:31], v[32:33] op_sel_hi:[1,0]
	v_pk_mul_f32 v[36:37], v[144:145], v[26:27]
	v_pk_mul_f32 v[26:27], v[146:147], v[24:25]
	v_cvt_pk_bf16_f32 v24, v28, v29
	v_add_co_u32_e32 v28, vcc, s2, v160
	v_pk_mul_f32 v[30:31], v[148:149], v[30:31]
	s_nop 0
	v_addc_co_u32_e32 v29, vcc, 0, v161, vcc
	v_cvt_pk_bf16_f32 v25, v30, v31
	v_pk_mul_f32 v[16:17], v[16:17], v[32:33] op_sel_hi:[1,0]
	v_pk_mul_f32 v[18:19], v[18:19], v[32:33] op_sel_hi:[1,0]
	v_cvt_pk_bf16_f32 v26, v26, v27
	v_cvt_pk_bf16_f32 v27, v36, v37
	global_store_dwordx4 v[28:29], v[24:27], off
	v_pk_mul_f32 v[20:21], v[20:21], v[32:33] op_sel_hi:[1,0]
	v_pk_mul_f32 v[22:23], v[22:23], v[32:33] op_sel_hi:[1,0]
	v_pk_mul_f32 v[24:25], v[152:153], v[18:19]
	v_pk_mul_f32 v[18:19], v[154:155], v[16:17]
	v_pk_mul_f32 v[22:23], v[156:157], v[22:23]
	v_pk_mul_f32 v[20:21], v[158:159], v[20:21]
	s_mov_b32 s2, 0x58000
	v_cvt_pk_bf16_f32 v16, v20, v21
	v_cvt_pk_bf16_f32 v17, v22, v23
	v_cvt_pk_bf16_f32 v18, v18, v19
	v_cvt_pk_bf16_f32 v19, v24, v25
	global_store_dwordx4 v[34:35], v[16:19], off offset:64
	s_nop 1
	v_pk_mul_f32 v[16:17], v[14:15], v[14:15]
	v_pk_mul_f32 v[18:19], v[12:13], v[12:13]
	s_nop 0
	v_pk_mov_b32 v[20:21], v[18:19], v[16:17] op_sel:[1,0]
	v_mov_b32_e32 v19, v17
	v_pk_add_f32 v[16:17], v[20:21], v[18:19]
	v_pk_mul_f32 v[18:19], v[10:11], v[10:11]
	v_pk_mul_f32 v[20:21], v[8:9], v[8:9]
	v_pk_add_f32 v[16:17], v[16:17], v[16:17] op_sel:[0,1] op_sel_hi:[1,0]
	v_pk_mov_b32 v[22:23], v[20:21], v[18:19] op_sel:[1,0]
	v_mov_b32_e32 v21, v19
	v_pk_add_f32 v[18:19], v[22:23], v[20:21]
	v_mul_f32_e32 v20, v0, v0
	v_mul_f32_e32 v21, v1, v1
	v_pk_add_f32 v[18:19], v[18:19], v[18:19] op_sel:[0,1] op_sel_hi:[1,0]
	v_mov_b32_e32 v17, v20
	v_mov_b32_e32 v19, v21
	v_pk_add_f32 v[16:17], v[16:17], v[18:19]
	v_mul_f32_e32 v18, v5, v5
	v_mul_f32_e32 v20, v7, v7
	v_mul_f32_e32 v22, v2, v2
	v_mul_f32_e32 v23, v3, v3
	v_pk_fma_f32 v[18:19], v[4:5], v[4:5], v[18:19] op_sel_hi:[1,1,0]
	v_pk_fma_f32 v[20:21], v[6:7], v[6:7], v[20:21] op_sel_hi:[1,1,0]
	v_mov_b32_e32 v19, v22
	v_mov_b32_e32 v21, v23
	v_pk_add_f32 v[18:19], v[18:19], v[20:21]
	s_nop 0
	v_pk_add_f32 v[16:17], v[16:17], v[18:19]
	v_lshl_add_u64 v[18:19], v[160:161], 0, s[6:7]
	v_add_f32_e32 v16, v16, v17
	ds_bpermute_b32 v17, v168, v16
	s_mov_b64 s[6:7], s[24:25]
	s_waitcnt lgkmcnt(0)
	v_add_f32_e32 v16, v16, v17
	ds_bpermute_b32 v17, v48, v16
	s_waitcnt lgkmcnt(0)
	v_add_f32_e32 v16, v16, v17
	v_fmamk_f32 v16, v16, 0x3c800000, v223
	v_rsq_f32_e32 v16, v16
	s_nop 0
	v_pk_mul_f32 v[12:13], v[12:13], v[16:17] op_sel_hi:[1,0]
	s_nop 0
	v_pk_mul_f32 v[12:13], v[150:151], v[12:13]
	v_pk_mul_f32 v[8:9], v[8:9], v[16:17] op_sel_hi:[1,0]
	v_pk_mul_f32 v[10:11], v[10:11], v[16:17] op_sel_hi:[1,0]
	v_pk_mul_f32 v[14:15], v[14:15], v[16:17] op_sel_hi:[1,0]
	v_pk_mul_f32 v[20:21], v[144:145], v[10:11]
	v_pk_mul_f32 v[10:11], v[146:147], v[8:9]
	v_cvt_pk_bf16_f32 v8, v12, v13
	v_add_co_u32_e32 v12, vcc, s2, v160
	v_pk_mul_f32 v[14:15], v[148:149], v[14:15]
	s_nop 0
	v_addc_co_u32_e32 v13, vcc, 0, v161, vcc
	v_cvt_pk_bf16_f32 v9, v14, v15
	v_pk_mul_f32 v[0:1], v[0:1], v[16:17] op_sel_hi:[1,0]
	v_pk_mul_f32 v[2:3], v[2:3], v[16:17] op_sel_hi:[1,0]
	v_cvt_pk_bf16_f32 v10, v10, v11
	v_cvt_pk_bf16_f32 v11, v20, v21
	global_store_dwordx4 v[12:13], v[8:11], off
	v_pk_mul_f32 v[4:5], v[4:5], v[16:17] op_sel_hi:[1,0]
	v_pk_mul_f32 v[6:7], v[6:7], v[16:17] op_sel_hi:[1,0]
	v_pk_mul_f32 v[8:9], v[152:153], v[2:3]
	v_pk_mul_f32 v[2:3], v[154:155], v[0:1]
	s_and_b64 vcc, exec, s[40:41]
	s_mov_b32 s2, s22
	v_pk_mul_f32 v[6:7], v[156:157], v[6:7]
	v_pk_mul_f32 v[4:5], v[158:159], v[4:5]
	s_nop 0
	v_cvt_pk_bf16_f32 v0, v4, v5
	v_cvt_pk_bf16_f32 v1, v6, v7
	v_cvt_pk_bf16_f32 v2, v2, v3
	v_cvt_pk_bf16_f32 v3, v8, v9
	global_store_dwordx4 v[18:19], v[0:3], off offset:64
	s_cbranch_vccz .LBB0_332
	s_waitcnt vmcnt(0)
	v_readlane_b32 s46, v254, 33
	v_readlane_b32 s48, v254, 35
	s_cmpk_gt_u32 s19, 0xff
	v_readlane_b32 s47, v254, 34
	v_readlane_b32 s49, v254, 36
	s_cbranch_scc1 .LBB0_339
	s_barrier

; #define PG8_STAGE(bufoff, gbase, voff) do { _Pragma("unroll") for (int _i = 0; _i < 2; ++_i) \
;         __builtin_amdgcn_global_load_lds((const unsigned*)((const char*)(gbase) + (voff)[_i]), (PG8_LAS unsigned*)(lds + (bufoff) + ldsw + _i * 8192), 16, 0, 0); } while (0)
; #define PG8_LDA(dst, b, h) do { _Pragma("unroll") for (int m = 0; m < 4; ++m) _Pragma("unroll") for (int k = 0; k < 2; ++k) dst[m][k] = *(const PG8_LAS bf16x8*)(lds + PG8_SA(b, h) + aoff + m * 2048 + k * 1024); } while (0)
; #define PG8_LDB(dst, b, h) do { _Pragma("unroll") for (int n = 0; n < 2; ++n) _Pragma("unroll") for (int k = 0; k < 2; ++k) dst[n][k] = *(const PG8_LAS bf16x8*)(lds + PG8_SB(b, h) + boff + n * 2048 + k * 1024); } while (0)
; #define PG8_MMA(ai, bj, At, Bt) do { __builtin_amdgcn_s_setprio(1); _Pragma("unroll") for (int m = 0; m < 4; ++m) _Pragma("unroll") for (int n = 0; n < 2; ++n) _Pragma("unroll") for (int k = 0; k < 2; ++k) \
;         acc[ai][bj][m][n] = __builtin_amdgcn_mfma_f32_16x16x32_bf16(Bt[n][k], At[m][k], acc[ai][bj][m][n], 0, 0, 0); __builtin_amdgcn_s_setprio(0); } while (0)
; #define PG8_WAIT_V(n) asm volatile("s_waitcnt vmcnt(" #n ")" ::: "memory")
; #define PG8_WAIT_L(n) asm volatile("s_waitcnt lgkmcnt(" #n ")" ::: "memory")
; #define PG8_BAR __builtin_amdgcn_s_barrier()
; #define PG8_SCHED __builtin_amdgcn_sched_barrier(0)
; template <class Epi, class Sched>
; __device__ __forceinline__ void gemm_phase(PG8_LAS unsigned char* lds, const Gemm g, const Sched& S, const Epi& E) {
;     ...
;             PG8_LDB(B0, 0, 0); PG8_SCHED; PG8_LDA(At, 0, 0); PG8_STAGE(PG8_SA(1, 1), a1 + hstep, voffA);
;             PG8_WAIT_L(8); PG8_BAR; PG8_WAIT_L(0); PG8_MMA(0, 0, At, B0); PG8_BAR; PG8_SCHED;
;             PG8_LDB(B1, 0, 1); PG8_STAGE(PG8_SB(0, 0), b2, voffB);
;             PG8_BAR; PG8_WAIT_L(0); PG8_MMA(0, 1, At, B1); PG8_BAR;
;             PG8_LDA(At, 0, 1); PG8_STAGE(PG8_SA(0, 0), a2, voffA);
;             PG8_BAR; PG8_WAIT_L(0); PG8_MMA(1, 0, At, B0); PG8_BAR; PG8_SCHED;
;             PG8_STAGE(PG8_SB(0, 1), b2 + hstep, voffB);
;             PG8_WAIT_V(6); PG8_BAR; PG8_MMA(1, 1, At, B1); PG8_BAR;
;             PG8_LDB(B0, 1, 0); PG8_SCHED; PG8_LDA(At, 1, 0); PG8_STAGE(PG8_SA(0, 1), a2 + hstep, voffA);
;             PG8_WAIT_L(8); PG8_BAR; PG8_WAIT_L(0); PG8_MMA(0, 0, At, B0); PG8_BAR; PG8_SCHED;
.LBB0_388:
	s_add_u32 s12, s6, 0xfffc0080
	s_addc_u32 s13, s7, -1
	s_add_i32 s22, 0, 0x10000
	v_add_u32_e32 v48, s22, v250
	ds_read_b128 v[130:133], v48
	ds_read_b128 v[134:137], v48 offset:1024
	ds_read_b128 v[138:141], v48 offset:2048
	ds_read_b128 v[142:145], v48 offset:3072
	s_cmp_eq_u32 s30, 12
	s_cselect_b32 s17, s9, s13
	s_cselect_b32 s16, s8, s12
	s_cselect_b32 s13, s3, s29
	s_cselect_b32 s12, s26, s27
	v_lshl_add_u64 v[192:193], s[6:7], 0, v[184:185]
	s_add_i32 m0, s37, 0xc000
	ds_read_b128 v[146:149], v242
	ds_read_b128 v[150:153], v242 offset:1024
	ds_read_b128 v[154:157], v242 offset:2048
	ds_read_b128 v[158:161], v242 offset:3072
	ds_read_b128 v[162:165], v242 offset:4096
	ds_read_b128 v[166:169], v242 offset:5120
	ds_read_b128 v[170:173], v242 offset:6144
	ds_read_b128 v[188:191], v242 offset:7168
	global_load_lds_dwordx4 v[192:193], off
	v_lshl_add_u64 v[192:193], s[6:7], 0, v[186:187]
	s_add_i32 m0, s37, 0xe000
	s_nop 0
	global_load_lds_dwordx4 v[192:193], off
	s_waitcnt lgkmcnt(8)
	s_barrier
	s_setprio 1
	s_waitcnt lgkmcnt(7)
	v_mfma_f32_16x16x32_bf16 v[126:129], v[130:133], v[146:149], v[126:129]
	v_mfma_f32_16x16x32_bf16 v[62:65], v[138:141], v[146:149], v[62:65]
	s_waitcnt lgkmcnt(5)
	v_mfma_f32_16x16x32_bf16 v[118:121], v[130:133], v[154:157], v[118:121]
	v_mfma_f32_16x16x32_bf16 v[54:57], v[138:141], v[154:157], v[54:57]
	s_waitcnt lgkmcnt(3)
	v_mfma_f32_16x16x32_bf16 v[110:113], v[130:133], v[162:165], v[110:113]
	v_mfma_f32_16x16x32_bf16 v[44:47], v[138:141], v[162:165], v[44:47]
	s_waitcnt lgkmcnt(1)
	v_mfma_f32_16x16x32_bf16 v[102:105], v[130:133], v[170:173], v[102:105]
	v_mfma_f32_16x16x32_bf16 v[36:39], v[138:141], v[170:173], v[36:39]
	v_mfma_f32_16x16x32_bf16 v[126:129], v[134:137], v[150:153], v[126:129]
	v_mfma_f32_16x16x32_bf16 v[62:65], v[142:145], v[150:153], v[62:65]
	v_mfma_f32_16x16x32_bf16 v[118:121], v[134:137], v[158:161], v[118:121]
	v_mfma_f32_16x16x32_bf16 v[54:57], v[142:145], v[158:161], v[54:57]
	v_mfma_f32_16x16x32_bf16 v[110:113], v[134:137], v[166:169], v[110:113]
	v_mfma_f32_16x16x32_bf16 v[44:47], v[142:145], v[166:169], v[44:47]
	s_waitcnt lgkmcnt(0)
	v_mfma_f32_16x16x32_bf16 v[102:105], v[134:137], v[188:191], v[102:105]
	v_mfma_f32_16x16x32_bf16 v[36:39], v[142:145], v[188:191], v[36:39]
	s_setprio 0
	s_barrier
	s_add_i32 s31, 0, 0x14000
	s_add_i32 s22, s22, s36
	v_add_u32_e32 v48, s31, v250
	v_lshl_add_u64 v[208:209], s[12:13], 0, v[178:179]
	s_mov_b32 m0, s22
	ds_read_b128 v[192:195], v48
	ds_read_b128 v[196:199], v48 offset:1024
	ds_read_b128 v[200:203], v48 offset:2048
	ds_read_b128 v[204:207], v48 offset:3072
	global_load_lds_dwordx4 v[208:209], off
	v_lshl_add_u64 v[210:211], s[12:13], 0, v[182:183]
	s_add_i32 m0, s22, 0x2000
	s_nop 0
	global_load_lds_dwordx4 v[210:211], off
	s_barrier
	s_setprio 1
	s_waitcnt lgkmcnt(3)
	v_mfma_f32_16x16x32_bf16 v[122:125], v[192:195], v[146:149], v[122:125]
	s_waitcnt lgkmcnt(1)
	v_mfma_f32_16x16x32_bf16 v[58:61], v[200:203], v[146:149], v[58:61]
	v_mfma_f32_16x16x32_bf16 v[114:117], v[192:195], v[154:157], v[114:117]
	v_mfma_f32_16x16x32_bf16 v[50:53], v[200:203], v[154:157], v[50:53]
	v_mfma_f32_16x16x32_bf16 v[106:109], v[192:195], v[162:165], v[106:109]
	v_mfma_f32_16x16x32_bf16 v[40:43], v[200:203], v[162:165], v[40:43]
	v_mfma_f32_16x16x32_bf16 v[98:101], v[192:195], v[170:173], v[98:101]
	v_mfma_f32_16x16x32_bf16 v[32:35], v[200:203], v[170:173], v[32:35]
	v_mfma_f32_16x16x32_bf16 v[122:125], v[196:199], v[150:153], v[122:125]
	s_waitcnt lgkmcnt(0)
	v_mfma_f32_16x16x32_bf16 v[58:61], v[204:207], v[150:153], v[58:61]
	v_mfma_f32_16x16x32_bf16 v[114:117], v[196:199], v[158:161], v[114:117]
	v_mfma_f32_16x16x32_bf16 v[50:53], v[204:207], v[158:161], v[50:53]
	v_mfma_f32_16x16x32_bf16 v[106:109], v[196:199], v[166:169], v[106:109]
	v_mfma_f32_16x16x32_bf16 v[40:43], v[204:207], v[166:169], v[40:43]
	v_mfma_f32_16x16x32_bf16 v[98:101], v[196:199], v[188:191], v[98:101]
	v_mfma_f32_16x16x32_bf16 v[32:35], v[204:207], v[188:191], v[32:35]
	s_setprio 0
	s_mov_b32 m0, s37
	v_lshl_add_u64 v[212:213], s[16:17], 0, v[176:177]
	s_barrier
	ds_read_b128 v[146:149], v242 offset:16384
	ds_read_b128 v[150:153], v242 offset:17408
	ds_read_b128 v[154:157], v242 offset:18432
	ds_read_b128 v[158:161], v242 offset:19456
	ds_read_b128 v[162:165], v242 offset:20480
	ds_read_b128 v[166:169], v242 offset:21504
	ds_read_b128 v[170:173], v242 offset:22528
	ds_read_b128 v[188:191], v242 offset:23552
	global_load_lds_dwordx4 v[212:213], off
	v_lshl_add_u64 v[214:215], s[16:17], 0, v[180:181]
	s_mov_b32 m0, s10
	s_nop 0
	global_load_lds_dwordx4 v[214:215], off
	s_barrier
	s_setprio 1
	s_waitcnt lgkmcnt(7)
	v_mfma_f32_16x16x32_bf16 v[94:97], v[130:133], v[146:149], v[94:97]
	v_mfma_f32_16x16x32_bf16 v[28:31], v[138:141], v[146:149], v[28:31]
	s_waitcnt lgkmcnt(5)
	v_mfma_f32_16x16x32_bf16 v[86:89], v[130:133], v[154:157], v[86:89]
	v_mfma_f32_16x16x32_bf16 v[20:23], v[138:141], v[154:157], v[20:23]
	s_waitcnt lgkmcnt(3)
	v_mfma_f32_16x16x32_bf16 v[78:81], v[130:133], v[162:165], v[78:81]
	v_mfma_f32_16x16x32_bf16 v[12:15], v[138:141], v[162:165], v[12:15]
	s_waitcnt lgkmcnt(1)
	v_mfma_f32_16x16x32_bf16 v[70:73], v[130:133], v[170:173], v[70:73]
	v_mfma_f32_16x16x32_bf16 v[4:7], v[138:141], v[170:173], v[4:7]
	v_mfma_f32_16x16x32_bf16 v[94:97], v[134:137], v[150:153], v[94:97]
	v_mfma_f32_16x16x32_bf16 v[28:31], v[142:145], v[150:153], v[28:31]
	v_mfma_f32_16x16x32_bf16 v[86:89], v[134:137], v[158:161], v[86:89]
	v_mfma_f32_16x16x32_bf16 v[20:23], v[142:145], v[158:161], v[20:23]
	v_mfma_f32_16x16x32_bf16 v[78:81], v[134:137], v[166:169], v[78:81]
	v_mfma_f32_16x16x32_bf16 v[12:15], v[142:145], v[166:169], v[12:15]
	s_waitcnt lgkmcnt(0)
	v_mfma_f32_16x16x32_bf16 v[70:73], v[134:137], v[188:191], v[70:73]
	v_mfma_f32_16x16x32_bf16 v[4:7], v[142:145], v[188:191], v[4:7]
	s_setprio 0
	s_barrier
; #define PG8_STAGE(bufoff, gbase, voff) do { _Pragma("unroll") for (int _i = 0; _i < 2; ++_i) \
;         __builtin_amdgcn_global_load_lds((const unsigned*)((const char*)(gbase) + (voff)[_i]), (PG8_LAS unsigned*)(lds + (bufoff) + ldsw + _i * 8192), 16, 0, 0); } while (0)
; #define PG8_LDA(dst, b, h) do { _Pragma("unroll") for (int m = 0; m < 4; ++m) _Pragma("unroll") for (int k = 0; k < 2; ++k) dst[m][k] = *(const PG8_LAS bf16x8*)(lds + PG8_SA(b, h) + aoff + m * 2048 + k * 1024); } while (0)
; #define PG8_LDB(dst, b, h) do { _Pragma("unroll") for (int n = 0; n < 2; ++n) _Pragma("unroll") for (int k = 0; k < 2; ++k) dst[n][k] = *(const PG8_LAS bf16x8*)(lds + PG8_SB(b, h) + boff + n * 2048 + k * 1024); } while (0)
; #define PG8_MMA(ai, bj, At, Bt) do { __builtin_amdgcn_s_setprio(1); _Pragma("unroll") for (int m = 0; m < 4; ++m) _Pragma("unroll") for (int n = 0; n < 2; ++n) _Pragma("unroll") for (int k = 0; k < 2; ++k) \
;         acc[ai][bj][m][n] = __builtin_amdgcn_mfma_f32_16x16x32_bf16(Bt[n][k], At[m][k], acc[ai][bj][m][n], 0, 0, 0); __builtin_amdgcn_s_setprio(0); } while (0)
; #define PG8_WAIT_V(n) asm volatile("s_waitcnt vmcnt(" #n ")" ::: "memory")
; #define PG8_WAIT_L(n) asm volatile("s_waitcnt lgkmcnt(" #n ")" ::: "memory")
; #define PG8_BAR __builtin_amdgcn_s_barrier()
; #define PG8_SCHED __builtin_amdgcn_sched_barrier(0)
; template <class Epi, class Sched>
; __device__ __forceinline__ void gemm_phase(PG8_LAS unsigned char* lds, const Gemm g, const Sched& S, const Epi& E) {
;     ...
;             PG8_STAGE(PG8_SB(0, 1), b2 + hstep, voffB);
;             PG8_WAIT_V(6); PG8_BAR; PG8_MMA(1, 1, At, B1); PG8_BAR;
;             PG8_LDB(B0, 1, 0); PG8_SCHED; PG8_LDA(At, 1, 0); PG8_STAGE(PG8_SA(0, 1), a2 + hstep, voffA);
;             PG8_WAIT_L(8); PG8_BAR; PG8_WAIT_L(0); PG8_MMA(0, 0, At, B0); PG8_BAR; PG8_SCHED;
;             PG8_LDB(B1, 1, 1); PG8_STAGE(PG8_SB(1, 0), b3, voffB);
;             PG8_BAR; PG8_WAIT_L(0); PG8_MMA(0, 1, At, B1); PG8_BAR;
;             PG8_LDA(At, 1, 1); PG8_STAGE(PG8_SA(1, 0), a3, voffA);
;             PG8_BAR; PG8_WAIT_L(0); PG8_MMA(1, 0, At, B0); PG8_BAR; PG8_SCHED;
	s_add_u32 s22, s12, 0x40000
	s_addc_u32 s23, s13, 0
	s_add_i32 s31, s31, s36
	v_lshl_add_u64 v[130:131], s[22:23], 0, v[178:179]
	s_mov_b32 m0, s31
	s_nop 0
	global_load_lds_dwordx4 v[130:131], off
	v_lshl_add_u64 v[130:131], s[22:23], 0, v[182:183]
	s_add_i32 m0, s31, 0x2000
	s_nop 0
	global_load_lds_dwordx4 v[130:131], off
	s_waitcnt vmcnt(6)
	s_barrier
	s_setprio 1
	v_mfma_f32_16x16x32_bf16 v[90:93], v[192:195], v[146:149], v[90:93]
	v_mfma_f32_16x16x32_bf16 v[24:27], v[200:203], v[146:149], v[24:27]
	v_mfma_f32_16x16x32_bf16 v[82:85], v[192:195], v[154:157], v[82:85]
	v_mfma_f32_16x16x32_bf16 v[16:19], v[200:203], v[154:157], v[16:19]
	v_mfma_f32_16x16x32_bf16 v[74:77], v[192:195], v[162:165], v[74:77]
	v_mfma_f32_16x16x32_bf16 v[8:11], v[200:203], v[162:165], v[8:11]
	v_mfma_f32_16x16x32_bf16 v[66:69], v[192:195], v[170:173], v[66:69]
	v_mfma_f32_16x16x32_bf16 v[0:3], v[200:203], v[170:173], v[0:3]
	v_mfma_f32_16x16x32_bf16 v[90:93], v[196:199], v[150:153], v[90:93]
	v_mfma_f32_16x16x32_bf16 v[24:27], v[204:207], v[150:153], v[24:27]
	v_mfma_f32_16x16x32_bf16 v[82:85], v[196:199], v[158:161], v[82:85]
	v_mfma_f32_16x16x32_bf16 v[16:19], v[204:207], v[158:161], v[16:19]
	v_mfma_f32_16x16x32_bf16 v[74:77], v[196:199], v[166:169], v[74:77]
	v_mfma_f32_16x16x32_bf16 v[8:11], v[204:207], v[166:169], v[8:11]
	v_mfma_f32_16x16x32_bf16 v[66:69], v[196:199], v[188:191], v[66:69]
	v_mfma_f32_16x16x32_bf16 v[0:3], v[204:207], v[188:191], v[0:3]
	s_setprio 0
	s_add_i32 s22, 0, 0x18000
	v_add_u32_e32 v48, s22, v250
	s_barrier
	ds_read_b128 v[130:133], v48
	ds_read_b128 v[134:137], v48 offset:1024
	ds_read_b128 v[138:141], v48 offset:2048
	ds_read_b128 v[142:145], v48 offset:3072
	s_add_u32 s16, s16, 0x40000
	s_addc_u32 s17, s17, 0
	s_mov_b32 m0, s11
	v_lshl_add_u64 v[192:193], s[16:17], 0, v[176:177]
	ds_read_b128 v[146:149], v242 offset:32768
	ds_read_b128 v[150:153], v242 offset:33792
	ds_read_b128 v[154:157], v242 offset:34816
	ds_read_b128 v[158:161], v242 offset:35840
	ds_read_b128 v[162:165], v242 offset:36864
	ds_read_b128 v[166:169], v242 offset:37888
	ds_read_b128 v[170:173], v242 offset:38912
	ds_read_b128 v[188:191], v242 offset:39936
	global_load_lds_dwordx4 v[192:193], off
	v_lshl_add_u64 v[192:193], s[16:17], 0, v[180:181]
	s_mov_b32 m0, s24
	s_nop 0
	global_load_lds_dwordx4 v[192:193], off
	s_waitcnt lgkmcnt(8)
	s_barrier
	s_setprio 1
	s_waitcnt lgkmcnt(7)
	v_mfma_f32_16x16x32_bf16 v[126:129], v[130:133], v[146:149], v[126:129]
	v_mfma_f32_16x16x32_bf16 v[62:65], v[138:141], v[146:149], v[62:65]
	s_waitcnt lgkmcnt(5)
	v_mfma_f32_16x16x32_bf16 v[118:121], v[130:133], v[154:157], v[118:121]
	v_mfma_f32_16x16x32_bf16 v[54:57], v[138:141], v[154:157], v[54:57]
	s_waitcnt lgkmcnt(3)
	v_mfma_f32_16x16x32_bf16 v[110:113], v[130:133], v[162:165], v[110:113]
	v_mfma_f32_16x16x32_bf16 v[44:47], v[138:141], v[162:165], v[44:47]
	s_waitcnt lgkmcnt(1)
	v_mfma_f32_16x16x32_bf16 v[102:105], v[130:133], v[170:173], v[102:105]
	v_mfma_f32_16x16x32_bf16 v[36:39], v[138:141], v[170:173], v[36:39]
	v_mfma_f32_16x16x32_bf16 v[126:129], v[134:137], v[150:153], v[126:129]
	v_mfma_f32_16x16x32_bf16 v[62:65], v[142:145], v[150:153], v[62:65]
	v_mfma_f32_16x16x32_bf16 v[118:121], v[134:137], v[158:161], v[118:121]
	v_mfma_f32_16x16x32_bf16 v[54:57], v[142:145], v[158:161], v[54:57]
	v_mfma_f32_16x16x32_bf16 v[110:113], v[134:137], v[166:169], v[110:113]
	v_mfma_f32_16x16x32_bf16 v[44:47], v[142:145], v[166:169], v[44:47]
	s_waitcnt lgkmcnt(0)
	v_mfma_f32_16x16x32_bf16 v[102:105], v[134:137], v[188:191], v[102:105]
	v_mfma_f32_16x16x32_bf16 v[36:39], v[142:145], v[188:191], v[36:39]
	s_setprio 0
	s_barrier
	s_add_i32 s16, 0, 0x1c000
	s_add_i32 s17, s22, s36
	v_add_u32_e32 v48, s16, v250
	v_lshl_add_u64 v[208:209], v[208:209], 0, s[0:1]
	s_mov_b32 m0, s17
	ds_read_b128 v[192:195], v48
	ds_read_b128 v[196:199], v48 offset:1024
	ds_read_b128 v[200:203], v48 offset:2048
	ds_read_b128 v[204:207], v48 offset:3072
	global_load_lds_dwordx4 v[208:209], off
	v_lshl_add_u64 v[208:209], v[210:211], 0, s[0:1]
	s_add_i32 m0, s17, 0x2000
	s_nop 0
	global_load_lds_dwordx4 v[208:209], off
	s_barrier
	s_setprio 1
	s_waitcnt lgkmcnt(3)
	v_mfma_f32_16x16x32_bf16 v[122:125], v[192:195], v[146:149], v[122:125]
	s_waitcnt lgkmcnt(1)
	v_mfma_f32_16x16x32_bf16 v[58:61], v[200:203], v[146:149], v[58:61]
	v_mfma_f32_16x16x32_bf16 v[114:117], v[192:195], v[154:157], v[114:117]
	v_mfma_f32_16x16x32_bf16 v[50:53], v[200:203], v[154:157], v[50:53]
	v_mfma_f32_16x16x32_bf16 v[106:109], v[192:195], v[162:165], v[106:109]
	v_mfma_f32_16x16x32_bf16 v[40:43], v[200:203], v[162:165], v[40:43]
	v_mfma_f32_16x16x32_bf16 v[98:101], v[192:195], v[170:173], v[98:101]
	v_mfma_f32_16x16x32_bf16 v[32:35], v[200:203], v[170:173], v[32:35]
	v_mfma_f32_16x16x32_bf16 v[122:125], v[196:199], v[150:153], v[122:125]
	s_waitcnt lgkmcnt(0)
	v_mfma_f32_16x16x32_bf16 v[58:61], v[204:207], v[150:153], v[58:61]
	v_mfma_f32_16x16x32_bf16 v[114:117], v[196:199], v[158:161], v[114:117]
	v_mfma_f32_16x16x32_bf16 v[50:53], v[204:207], v[158:161], v[50:53]
	v_mfma_f32_16x16x32_bf16 v[106:109], v[196:199], v[166:169], v[106:109]
	v_mfma_f32_16x16x32_bf16 v[40:43], v[204:207], v[166:169], v[40:43]
	v_mfma_f32_16x16x32_bf16 v[98:101], v[196:199], v[188:191], v[98:101]
	v_mfma_f32_16x16x32_bf16 v[32:35], v[204:207], v[188:191], v[32:35]
	s_setprio 0
	s_mov_b32 m0, s25
	v_lshl_add_u64 v[208:209], v[212:213], 0, s[0:1]
	s_barrier
; #define LAS __attribute__((address_space(3)))
; #define PG8_STAGE(bufoff, gbase, voff) do { _Pragma("unroll") for (int _i = 0; _i < 2; ++_i) \
;         __builtin_amdgcn_global_load_lds((const unsigned*)((const char*)(gbase) + (voff)[_i]), (PG8_LAS unsigned*)(lds + (bufoff) + ldsw + _i * 8192), 16, 0, 0); } while (0)
; #define PG8_LDA(dst, b, h) do { _Pragma("unroll") for (int m = 0; m < 4; ++m) _Pragma("unroll") for (int k = 0; k < 2; ++k) dst[m][k] = *(const PG8_LAS bf16x8*)(lds + PG8_SA(b, h) + aoff + m * 2048 + k * 1024); } while (0)
; #define PG8_LDB(dst, b, h) do { _Pragma("unroll") for (int n = 0; n < 2; ++n) _Pragma("unroll") for (int k = 0; k < 2; ++k) dst[n][k] = *(const PG8_LAS bf16x8*)(lds + PG8_SB(b, h) + boff + n * 2048 + k * 1024); } while (0)
; #define PG8_WAIT_V(n) asm volatile("s_waitcnt vmcnt(" #n ")" ::: "memory")
; #define PG8_BAR __builtin_amdgcn_s_barrier()
; template <class Epi, class Sched>
; __device__ __forceinline__ void gemm_phase(PG8_LAS unsigned char* lds, const Gemm g, const Sched& S, const Epi& E) {
;     ...
;             PG8_LDB(B0, 1, 0); PG8_SCHED; PG8_LDA(At, 1, 0); PG8_STAGE(PG8_SA(0, 1), a2 + hstep, voffA);
;             PG8_WAIT_L(8); PG8_BAR; PG8_WAIT_L(0); PG8_MMA(0, 0, At, B0); PG8_BAR; PG8_SCHED;
;             PG8_LDB(B1, 1, 1); PG8_STAGE(PG8_SB(1, 0), b3, voffB);
;             PG8_BAR; PG8_WAIT_L(0); PG8_MMA(0, 1, At, B1); PG8_BAR;
;             PG8_LDA(At, 1, 1); PG8_STAGE(PG8_SA(1, 0), a3, voffA);
;             PG8_BAR; PG8_WAIT_L(0); PG8_MMA(1, 0, At, B0); PG8_BAR; PG8_SCHED;
;             PG8_STAGE(PG8_SB(1, 1), b3 + hstep, voffB);
;             PG8_WAIT_V(6); PG8_BAR; PG8_MMA(1, 1, At, B1); PG8_BAR;
;         }
;     __device__ __forceinline__ void operator()(const f32x4 (&acc)[2][2][4][2], const pg8::Unit& u, int wr, int wc, int fr, int fq) const {
;     ...
;         for (int ai = 0; ai < 2; ++ai) { const int s = 2 * ai + wr;
;             if (fr == 0) { LAS float* p = xb + (s * 2 + 0) * 256 + cl; *(LAS f32x4*)p = acc[ai][0][0][0]; *(LAS f32x4*)(p + 4) = acc[ai][0][0][1]; *(LAS f32x4*)(p + 128) = acc[ai][1][0][0]; *(LAS f32x4*)(p + 132) = acc[ai][1][0][1]; }
;             if (fr == 15) { LAS float* p = xb + (s * 2 + 1) * 256 + cl; *(LAS f32x4*)p = acc[ai][0][3][0]; *(LAS f32x4*)(p + 4) = acc[ai][0][3][1]; *(LAS f32x4*)(p + 128) = acc[ai][1][3][0]; *(LAS f32x4*)(p + 132) = acc[ai][1][3][1]; } }
	ds_read_b128 v[146:149], v242 offset:49152
	ds_read_b128 v[150:153], v242 offset:50176
	ds_read_b128 v[154:157], v242 offset:51200
	ds_read_b128 v[158:161], v242 offset:52224
	ds_read_b128 v[162:165], v242 offset:53248
	ds_read_b128 v[166:169], v242 offset:54272
	ds_read_b128 v[170:173], v242 offset:55296
	ds_read_b128 v[188:191], v242 offset:56320
	global_load_lds_dwordx4 v[208:209], off
	v_lshl_add_u64 v[208:209], v[214:215], 0, s[0:1]
	s_mov_b32 m0, s18
	s_nop 0
	global_load_lds_dwordx4 v[208:209], off
	s_barrier
	s_setprio 1
	s_waitcnt lgkmcnt(7)
	v_mfma_f32_16x16x32_bf16 v[94:97], v[130:133], v[146:149], v[94:97]
	v_mfma_f32_16x16x32_bf16 v[28:31], v[138:141], v[146:149], v[28:31]
	s_waitcnt lgkmcnt(5)
	v_mfma_f32_16x16x32_bf16 v[86:89], v[130:133], v[154:157], v[86:89]
	v_mfma_f32_16x16x32_bf16 v[20:23], v[138:141], v[154:157], v[20:23]
	s_waitcnt lgkmcnt(3)
	v_mfma_f32_16x16x32_bf16 v[78:81], v[130:133], v[162:165], v[78:81]
	v_mfma_f32_16x16x32_bf16 v[12:15], v[138:141], v[162:165], v[12:15]
	s_waitcnt lgkmcnt(1)
	v_mfma_f32_16x16x32_bf16 v[70:73], v[130:133], v[170:173], v[70:73]
	v_mfma_f32_16x16x32_bf16 v[4:7], v[138:141], v[170:173], v[4:7]
	v_mfma_f32_16x16x32_bf16 v[94:97], v[134:137], v[150:153], v[94:97]
	v_mfma_f32_16x16x32_bf16 v[28:31], v[142:145], v[150:153], v[28:31]
	v_mfma_f32_16x16x32_bf16 v[86:89], v[134:137], v[158:161], v[86:89]
	v_mfma_f32_16x16x32_bf16 v[20:23], v[142:145], v[158:161], v[20:23]
	v_mfma_f32_16x16x32_bf16 v[78:81], v[134:137], v[166:169], v[78:81]
	v_mfma_f32_16x16x32_bf16 v[12:15], v[142:145], v[166:169], v[12:15]
	s_waitcnt lgkmcnt(0)
	v_mfma_f32_16x16x32_bf16 v[70:73], v[134:137], v[188:191], v[70:73]
	v_mfma_f32_16x16x32_bf16 v[4:7], v[142:145], v[188:191], v[4:7]
	s_setprio 0
	s_barrier
	s_add_u32 s12, s12, 0x40080
	s_addc_u32 s13, s13, 0
	s_add_i32 s16, s16, s36
	v_lshl_add_u64 v[130:131], s[12:13], 0, v[178:179]
	s_mov_b32 m0, s16
	s_nop 0
	global_load_lds_dwordx4 v[130:131], off
	v_lshl_add_u64 v[130:131], s[12:13], 0, v[182:183]
	s_add_i32 m0, s16, 0x2000
	s_nop 0
	global_load_lds_dwordx4 v[130:131], off
	s_waitcnt vmcnt(6)
	s_barrier
	s_setprio 1
	v_mfma_f32_16x16x32_bf16 v[90:93], v[192:195], v[146:149], v[90:93]
	v_mfma_f32_16x16x32_bf16 v[24:27], v[200:203], v[146:149], v[24:27]
	v_mfma_f32_16x16x32_bf16 v[82:85], v[192:195], v[154:157], v[82:85]
	v_mfma_f32_16x16x32_bf16 v[16:19], v[200:203], v[154:157], v[16:19]
	v_mfma_f32_16x16x32_bf16 v[74:77], v[192:195], v[162:165], v[74:77]
	v_mfma_f32_16x16x32_bf16 v[8:11], v[200:203], v[162:165], v[8:11]
	v_mfma_f32_16x16x32_bf16 v[66:69], v[192:195], v[170:173], v[66:69]
	v_mfma_f32_16x16x32_bf16 v[0:3], v[200:203], v[170:173], v[0:3]
	v_mfma_f32_16x16x32_bf16 v[90:93], v[196:199], v[150:153], v[90:93]
	v_mfma_f32_16x16x32_bf16 v[24:27], v[204:207], v[150:153], v[24:27]
	v_mfma_f32_16x16x32_bf16 v[82:85], v[196:199], v[158:161], v[82:85]
	v_mfma_f32_16x16x32_bf16 v[16:19], v[204:207], v[158:161], v[16:19]
	v_mfma_f32_16x16x32_bf16 v[74:77], v[196:199], v[166:169], v[74:77]
	v_mfma_f32_16x16x32_bf16 v[8:11], v[204:207], v[166:169], v[8:11]
	v_mfma_f32_16x16x32_bf16 v[66:69], v[196:199], v[188:191], v[66:69]
	v_mfma_f32_16x16x32_bf16 v[0:3], v[204:207], v[188:191], v[0:3]
	s_setprio 0
	s_add_i32 s30, s30, 2
	s_add_u32 s6, s6, 0x100
	s_addc_u32 s7, s7, 0
	s_add_u32 s27, s27, 0x100
	s_addc_u32 s29, s29, 0
	s_cmp_gt_u32 s30, 13
	s_barrier
	s_cbranch_scc0 .LBB0_388
	v_cmp_lt_i32_e32 vcc, 14, v175
	s_mov_b64 s[12:13], 0
	s_and_saveexec_b64 s[6:7], vcc
	s_xor_b64 s[6:7], exec, s[6:7]
	s_mov_b64 s[12:13], exec
	s_or_saveexec_b64 s[6:7], s[6:7]
	v_readlane_b32 s3, v254, 59
	v_mov_b64_e32 v[132:133], v[38:39]
	v_mov_b64_e32 v[136:137], v[104:105]
	v_mov_b64_e32 v[140:141], v[100:101]
	v_mov_b64_e32 v[144:145], v[34:35]
	v_mov_b32_e32 v48, s3
	v_mov_b64_e32 v[130:131], v[36:37]
	v_mov_b64_e32 v[134:135], v[102:103]
	v_mov_b64_e32 v[138:139], v[98:99]
	v_mov_b64_e32 v[142:143], v[32:33]
	s_xor_b64 exec, exec, s[6:7]
	s_cbranch_execz .LBB0_393
	v_readlane_b32 s3, v254, 58
	s_andn2_b64 s[12:13], s[12:13], exec
	s_and_b64 s[16:17], s[40:41], exec
	v_mov_b64_e32 v[132:133], v[64:65]
	v_mov_b64_e32 v[136:137], v[128:129]
	v_mov_b64_e32 v[140:141], v[124:125]
	v_mov_b64_e32 v[144:145], v[60:61]
	v_mov_b32_e32 v48, s3
	s_or_b64 s[12:13], s[12:13], s[16:17]
	v_mov_b64_e32 v[130:131], v[62:63]
	v_mov_b64_e32 v[134:135], v[126:127]
	v_mov_b64_e32 v[138:139], v[122:123]
	v_mov_b64_e32 v[142:143], v[58:59]
